# 64-deep full-line K-loop now in all eight regular GEMM loops (mix_out, moe_up, moe_down, conv_in x2, conv_out)
# speedup vs baseline: 1.2529x; 1.0094x over previous
.LBB0_601:
	s_lshr_b32 s2, s21, 3
	s_or_b32 s2, s2, s22
	s_lshl_b32 s28, s2, 18
	s_and_b32 s27, s21, 7
	v_or_b32_e32 v1, s28, v129
	s_lshl_b32 s2, s27, 18
	s_add_u32 s14, s16, s2
	v_or_b32_e32 v0, v1, v128
	v_readfirstlane_b32 s2, v148
	v_lshlrev_b32_e32 v130, 1, v0
	s_mov_b32 m0, s2
	v_readfirstlane_b32 s2, v157
	v_add_lshl_u32 v0, v1, v154, 1
	s_waitcnt vmcnt(0)
	s_barrier
	s_nop 0
	s_mov_b32 m0, s2
	v_readfirstlane_b32 s2, v158
	s_addc_u32 s15, s17, 0
	v_add_lshl_u32 v2, v1, v155, 1
	s_nop 0
	s_mov_b32 m0, s2
	v_readfirstlane_b32 s2, v159
	v_add_lshl_u32 v4, v1, v156, 1
	v_lshl_add_u64 v[6:7], s[14:15], 0, v[132:133]
	s_nop 0
	s_mov_b32 m0, s2
	v_readfirstlane_b32 s2, v160
	v_lshl_add_u64 v[136:137], v[6:7], 0, v[134:135]
	s_nop 0
	s_mov_b32 m0, s2
	v_readfirstlane_b32 s2, v161
	v_lshl_add_u64 v[138:139], s[0:1], 0, v[130:131]
	v_mov_b32_e32 v1, v131
	v_lshl_add_u64 v[146:147], v[136:137], 0, s[4:5]
	s_nop 0
	s_mov_b32 m0, s2
	v_readfirstlane_b32 s2, v162
	v_lshl_add_u64 v[140:141], s[0:1], 0, v[0:1]
	v_mov_b32_e32 v3, v131
	s_nop 0
	v_lshl_add_u64 v[0:1], v[138:139], 0, 64
	s_mov_b32 m0, s2
	v_readfirstlane_b32 s2, v163
	v_lshl_add_u64 v[142:143], s[0:1], 0, v[2:3]
	v_mov_b32_e32 v5, v131
	s_nop 0
	v_lshl_add_u64 v[0:1], v[140:141], 0, 64
	s_mov_b32 m0, s2
	v_readfirstlane_b32 s2, v164
	v_lshl_add_u64 v[144:145], s[0:1], 0, v[4:5]
	s_nop 0
	v_lshl_add_u64 v[0:1], v[142:143], 0, 64
	s_mov_b32 m0, s2
	v_readfirstlane_b32 s2, v165
	s_nop 0
	v_lshl_add_u64 v[0:1], v[144:145], 0, 64
	s_mov_b32 m0, s2
	v_readfirstlane_b32 s2, v166
	s_nop 0
	v_lshl_add_u64 v[0:1], v[136:137], 0, 64
	s_mov_b32 m0, s2
	v_readfirstlane_b32 s2, v167
	s_nop 0
	v_lshl_add_u64 v[0:1], v[136:137], 0, s[10:11]
	s_mov_b32 m0, s2
	s_mov_b32 s14, s3
	s_nop 0
	s_mov_b32 s15, 2
	s_mov_b32 s29, s3
	v_mov_b32_e32 v0, 0
	v_mov_b32_e32 v1, v131
	v_mov_b32_e32 v2, v131
	v_mov_b32_e32 v4, v131
	v_mov_b32_e32 v6, v131
	v_mov_b32_e32 v7, v131
	v_mov_b32_e32 v8, v131
	v_mov_b32_e32 v9, v131
	v_mov_b32_e32 v10, v131
	v_mov_b32_e32 v11, v131
	v_mov_b32_e32 v12, v131
	v_mov_b32_e32 v13, v131
	v_mov_b32_e32 v14, v131
	v_mov_b32_e32 v15, v131
	v_mov_b32_e32 v16, 0
	v_mov_b32_e32 v17, v131
	v_mov_b32_e32 v18, v131
	v_mov_b32_e32 v19, v131
	v_mov_b32_e32 v20, v131
	v_mov_b32_e32 v21, v131
	v_mov_b32_e32 v22, v131
	v_mov_b32_e32 v23, v131
	v_mov_b32_e32 v24, v131
	v_mov_b32_e32 v25, v131
	v_mov_b32_e32 v26, v131
	v_mov_b32_e32 v27, v131
	v_mov_b32_e32 v28, v131
	v_mov_b32_e32 v29, v131
	v_mov_b32_e32 v30, v131
	v_mov_b32_e32 v31, v131
	v_mov_b32_e32 v32, 0
	v_mov_b32_e32 v33, v131
	v_mov_b32_e32 v34, v131
	v_mov_b32_e32 v35, v131
	v_mov_b32_e32 v36, v131
	v_mov_b32_e32 v37, v131
	v_mov_b32_e32 v38, v131
	v_mov_b32_e32 v39, v131
	v_mov_b32_e32 v40, v131
	v_mov_b32_e32 v41, v131
	v_mov_b32_e32 v42, v131
	v_mov_b32_e32 v43, v131
	v_mov_b32_e32 v44, v131
	v_mov_b32_e32 v45, v131
	v_mov_b32_e32 v46, v131
	v_mov_b32_e32 v47, v131
	v_mov_b32_e32 v48, 0
	v_mov_b32_e32 v49, v131
	v_mov_b32_e32 v50, v131
	v_mov_b32_e32 v51, v131
	v_mov_b32_e32 v52, v131
	v_mov_b32_e32 v53, v131
	v_mov_b32_e32 v54, v131
	v_mov_b32_e32 v55, v131
	v_mov_b32_e32 v56, v131
	v_mov_b32_e32 v57, v131
	v_mov_b32_e32 v58, v131
	v_mov_b32_e32 v59, v131
	v_mov_b32_e32 v60, v131
	v_mov_b32_e32 v61, v131
	v_mov_b32_e32 v62, v131
	v_mov_b32_e32 v63, v131
	v_mov_b32_e32 v64, 0
	v_mov_b32_e32 v65, v131
	v_mov_b32_e32 v66, v131
	v_mov_b32_e32 v67, v131
	v_mov_b32_e32 v68, v131
	v_mov_b32_e32 v69, v131
	v_mov_b32_e32 v70, v131
	v_mov_b32_e32 v71, v131
	v_mov_b32_e32 v72, v131
	v_mov_b32_e32 v73, v131
	v_mov_b32_e32 v74, v131
	v_mov_b32_e32 v75, v131
	v_mov_b32_e32 v76, v131
	v_mov_b32_e32 v77, v131
	v_mov_b32_e32 v78, v131
	v_mov_b32_e32 v79, v131
	v_mov_b32_e32 v80, 0
	v_mov_b32_e32 v81, v131
	v_mov_b32_e32 v82, v131
	v_mov_b32_e32 v83, v131
	v_mov_b32_e32 v84, v131
	v_mov_b32_e32 v85, v131
	v_mov_b32_e32 v86, v131
	v_mov_b32_e32 v87, v131
	v_mov_b32_e32 v88, v131
	v_mov_b32_e32 v89, v131
	v_mov_b32_e32 v90, v131
	v_mov_b32_e32 v91, v131
	v_mov_b32_e32 v92, v131
	v_mov_b32_e32 v93, v131
	v_mov_b32_e32 v94, v131
	v_mov_b32_e32 v95, v131
	v_mov_b32_e32 v96, 0
	v_mov_b32_e32 v97, v131
	v_mov_b32_e32 v98, v131
	v_mov_b32_e32 v99, v131
	v_mov_b32_e32 v100, v131
	v_mov_b32_e32 v101, v131
	v_mov_b32_e32 v102, v131
	v_mov_b32_e32 v103, v131
	v_mov_b32_e32 v104, v131
	v_mov_b32_e32 v105, v131
	v_mov_b32_e32 v106, v131
	v_mov_b32_e32 v107, v131
	v_mov_b32_e32 v108, v131
	v_mov_b32_e32 v109, v131
	v_mov_b32_e32 v110, v131
	v_mov_b32_e32 v111, v131
	v_mov_b32_e32 v112, 0
	v_mov_b32_e32 v113, v131
	v_mov_b32_e32 v114, v131
	v_mov_b32_e32 v115, v131
	v_mov_b32_e32 v116, v131
	v_mov_b32_e32 v117, v131
	v_mov_b32_e32 v118, v131
	v_mov_b32_e32 v119, v131
	v_mov_b32_e32 v120, v131
	v_mov_b32_e32 v121, v131
	v_mov_b32_e32 v122, v131
	v_mov_b32_e32 v123, v131
	v_mov_b32_e32 v124, v131
	v_mov_b32_e32 v125, v131
	v_mov_b32_e32 v126, v131
	v_mov_b32_e32 v127, v131
	s_mov_b64 s[50:51], 0x80
	v_lshrrev_b32_e32 v174, 6, v180
	v_lshlrev_b32_e32 v184, 11, v174
	v_mov_b32_e32 v175, 0x12000
	ds_read_b64 v[176:177], v175
	v_and_b32_e32 v170, 63, v180
	v_readfirstlane_b32 s49, v184
	v_lshrrev_b32_e32 v171, 5, v170
	v_bfe_u32 v172, v170, 1, 3
	v_xor_b32_e32 v172, v171, v172
	v_and_b32_e32 v173, 31, v170
	v_lshlrev_b32_e32 v173, 7, v173
	v_lshrrev_b32_e32 v173, 3, v170
	v_lshlrev_b32_e32 v184, 4, v173
	v_add_u32_e32 v185, 0x80, v184
	v_and_b32_e32 v173, 7, v170
	v_lshrrev_b32_e32 v171, 4, v170
	v_xor_b32_e32 v171, v173, v171
	v_lshrrev_b32_e32 v173, 5, v170
	v_sub_u32_e32 v186, v171, v173
	v_xor_b32_e32 v171, 4, v171
	v_add_u32_e32 v173, 2, v173
	v_sub_u32_e32 v188, v171, v173
	v_lshlrev_b32_e32 v186, 4, v186
	v_ashrrev_i32_e32 v187, 31, v186
	v_lshlrev_b32_e32 v188, 4, v188
	v_ashrrev_i32_e32 v189, 31, v188
	ds_bpermute_b32 v244, v184, v136
	ds_bpermute_b32 v245, v184, v137
	ds_bpermute_b32 v246, v185, v136
	ds_bpermute_b32 v247, v185, v137
	ds_bpermute_b32 v248, v184, v146
	ds_bpermute_b32 v249, v184, v147
	ds_bpermute_b32 v250, v185, v146
	ds_bpermute_b32 v251, v185, v147
	s_waitcnt lgkmcnt(0)
	ds_bpermute_b32 v178, v184, v138
	ds_bpermute_b32 v179, v184, v139
	ds_bpermute_b32 v234, v185, v138
	ds_bpermute_b32 v235, v185, v139
	ds_bpermute_b32 v236, v184, v140
	ds_bpermute_b32 v237, v184, v141
	ds_bpermute_b32 v238, v185, v140
	ds_bpermute_b32 v239, v185, v141
	ds_bpermute_b32 v240, v184, v142
	ds_bpermute_b32 v241, v184, v143
	ds_bpermute_b32 v242, v185, v142
	ds_bpermute_b32 v243, v185, v143
	ds_bpermute_b32 v136, v184, v144
	ds_bpermute_b32 v137, v184, v145
	ds_bpermute_b32 v146, v185, v144
	ds_bpermute_b32 v147, v185, v145
	s_waitcnt lgkmcnt(0)
	v_readfirstlane_b32 s52, v176
	v_readfirstlane_b32 s53, v177
	v_and_b32_e32 v173, 31, v170
	v_lshlrev_b32_e32 v173, 7, v173
	v_lshrrev_b32_e32 v171, 1, v174
	v_lshl_add_u32 v138, v171, 14, v173
	v_and_b32_e32 v171, 1, v174
	v_lshl_add_u32 v142, v171, 13, v173
	v_add_u32_e32 v142, 0x10000, v142
	v_xor_b32_e32 v173, 6, v172
	v_lshl_add_u32 v141, v173, 4, v138
	v_lshl_add_u32 v145, v173, 4, v142
	v_xor_b32_e32 v173, 4, v172
	v_lshl_add_u32 v140, v173, 4, v138
	v_lshl_add_u32 v144, v173, 4, v142
	v_xor_b32_e32 v173, 2, v172
	v_lshl_add_u32 v139, v173, 4, v138
	v_lshl_add_u32 v143, v173, 4, v142
	v_xor_b32_e32 v173, 0, v172
	v_lshl_add_u32 v138, v173, 4, v138
	v_lshl_add_u32 v142, v173, 4, v142
	v_lshl_add_u64 v[178:179], v[178:179], 0, v[186:187]
	v_lshl_add_u64 v[234:235], v[234:235], 0, v[188:189]
	v_lshl_add_u64 v[236:237], v[236:237], 0, v[186:187]
	v_lshl_add_u64 v[238:239], v[238:239], 0, v[188:189]
	v_lshl_add_u64 v[240:241], v[240:241], 0, v[186:187]
	v_lshl_add_u64 v[242:243], v[242:243], 0, v[188:189]
	v_lshl_add_u64 v[136:137], v[136:137], 0, v[186:187]
	v_lshl_add_u64 v[146:147], v[146:147], 0, v[188:189]
	v_lshl_add_u64 v[244:245], v[244:245], 0, v[186:187]
	v_lshl_add_u64 v[246:247], v[246:247], 0, v[188:189]
	v_lshl_add_u64 v[248:249], v[248:249], 0, v[186:187]
	v_lshl_add_u64 v[250:251], v[250:251], 0, v[188:189]
	s_mov_b32 s54, s49
	s_add_i32 m0, s54, 0x0
	s_nop 0
	global_load_lds_dwordx4 v[178:179], off
	s_add_i32 m0, s54, 0x400
	v_lshl_add_u64 v[178:179], v[178:179], 0, s[50:51]
	global_load_lds_dwordx4 v[234:235], off
	s_add_i32 m0, s54, 0x2000
	v_lshl_add_u64 v[234:235], v[234:235], 0, s[50:51]
	global_load_lds_dwordx4 v[236:237], off
	s_add_i32 m0, s54, 0x2400
	v_lshl_add_u64 v[236:237], v[236:237], 0, s[50:51]
	global_load_lds_dwordx4 v[238:239], off
	s_add_i32 m0, s54, 0x4000
	v_lshl_add_u64 v[238:239], v[238:239], 0, s[50:51]
	global_load_lds_dwordx4 v[240:241], off
	s_add_i32 m0, s54, 0x4400
	v_lshl_add_u64 v[240:241], v[240:241], 0, s[50:51]
	global_load_lds_dwordx4 v[242:243], off
	s_add_i32 m0, s54, 0x6000
	v_lshl_add_u64 v[242:243], v[242:243], 0, s[50:51]
	global_load_lds_dwordx4 v[136:137], off
	s_add_i32 m0, s54, 0x6400
	v_lshl_add_u64 v[136:137], v[136:137], 0, s[50:51]
	global_load_lds_dwordx4 v[146:147], off
	v_lshl_add_u64 v[146:147], v[146:147], 0, s[50:51]
	s_add_i32 s54, s49, 0x10000
	s_add_i32 m0, s54, 0x0
	s_nop 0
	global_load_lds_dwordx4 v[244:245], off
	s_add_i32 m0, s54, 0x400
	v_lshl_add_u64 v[244:245], v[244:245], 0, s[50:51]
	global_load_lds_dwordx4 v[246:247], off
	s_add_i32 m0, s54, 0x2000
	v_lshl_add_u64 v[246:247], v[246:247], 0, s[50:51]
	global_load_lds_dwordx4 v[248:249], off
	s_add_i32 m0, s54, 0x2400
	v_lshl_add_u64 v[248:249], v[248:249], 0, s[50:51]
	global_load_lds_dwordx4 v[250:251], off
	v_lshl_add_u64 v[250:251], v[250:251], 0, s[50:51]
	s_mov_b32 s14, 0
	s_mov_b32 s15, 0
.Lg_ph5_top:
	s_waitcnt vmcnt(0)
	s_waitcnt lgkmcnt(0)
	s_barrier
	s_cmp_eq_u32 s14, 15
	s_cbranch_scc1 .Lg_ph5_noA
	s_xor_b32 s54, s15, 0x8000
	s_add_i32 s54, s54, s49
	s_add_i32 m0, s54, 0x0
	s_nop 0
	global_load_lds_dwordx4 v[178:179], off
	s_add_i32 m0, s54, 0x400
	v_lshl_add_u64 v[178:179], v[178:179], 0, s[50:51]
	global_load_lds_dwordx4 v[234:235], off
	s_add_i32 m0, s54, 0x2000
	v_lshl_add_u64 v[234:235], v[234:235], 0, s[50:51]
	global_load_lds_dwordx4 v[236:237], off
	s_add_i32 m0, s54, 0x2400
	v_lshl_add_u64 v[236:237], v[236:237], 0, s[50:51]
	global_load_lds_dwordx4 v[238:239], off
	s_add_i32 m0, s54, 0x4000
	v_lshl_add_u64 v[238:239], v[238:239], 0, s[50:51]
	global_load_lds_dwordx4 v[240:241], off
	s_add_i32 m0, s54, 0x4400
	v_lshl_add_u64 v[240:241], v[240:241], 0, s[50:51]
	global_load_lds_dwordx4 v[242:243], off
	s_add_i32 m0, s54, 0x6000
	v_lshl_add_u64 v[242:243], v[242:243], 0, s[50:51]
	global_load_lds_dwordx4 v[136:137], off
	s_add_i32 m0, s54, 0x6400
	v_lshl_add_u64 v[136:137], v[136:137], 0, s[50:51]
	global_load_lds_dwordx4 v[146:147], off
	v_lshl_add_u64 v[146:147], v[146:147], 0, s[50:51]
.Lg_ph5_noA:
	ds_read_b128 v[190:193], v142
	ds_read_b128 v[194:197], v142 offset:4096
	ds_read_b128 v[198:201], v143
	ds_read_b128 v[202:205], v143 offset:4096
	ds_read_b128 v[206:209], v144
	ds_read_b128 v[222:225], v144 offset:4096
	ds_read_b128 v[226:229], v145
	ds_read_b128 v[230:233], v145 offset:4096
	ds_read_b128 v[170:173], v138
	ds_read_b128 v[174:177], v138 offset:4096
	ds_read_b128 v[182:185], v138 offset:8192
	ds_read_b128 v[186:189], v138 offset:12288
	s_waitcnt lgkmcnt(4)
	s_barrier
	s_cmp_eq_u32 s14, 15
	s_cbranch_scc1 .Lg_ph5_noB
	s_add_i32 s54, s49, 0x10000
	s_add_i32 m0, s54, 0x0
	s_nop 0
	global_load_lds_dwordx4 v[244:245], off
	s_add_i32 m0, s54, 0x400
	v_lshl_add_u64 v[244:245], v[244:245], 0, s[50:51]
	global_load_lds_dwordx4 v[246:247], off
	s_add_i32 m0, s54, 0x2000
	v_lshl_add_u64 v[246:247], v[246:247], 0, s[50:51]
	global_load_lds_dwordx4 v[248:249], off
	s_add_i32 m0, s54, 0x2400
	v_lshl_add_u64 v[248:249], v[248:249], 0, s[50:51]
	global_load_lds_dwordx4 v[250:251], off
	v_lshl_add_u64 v[250:251], v[250:251], 0, s[50:51]
.Lg_ph5_noB:
	s_waitcnt lgkmcnt(3)
	v_mfma_f32_32x32x16_bf16 v[0:15], v[170:173], v[190:193], v[0:15]
	v_mfma_f32_32x32x16_bf16 v[16:31], v[170:173], v[194:197], v[16:31]
	ds_read_b128 v[170:173], v139
	s_waitcnt lgkmcnt(3)
	v_mfma_f32_32x32x16_bf16 v[32:47], v[174:177], v[190:193], v[32:47]
	v_mfma_f32_32x32x16_bf16 v[48:63], v[174:177], v[194:197], v[48:63]
	ds_read_b128 v[174:177], v139 offset:4096
	s_waitcnt lgkmcnt(3)
	v_mfma_f32_32x32x16_bf16 v[64:79], v[182:185], v[190:193], v[64:79]
	v_mfma_f32_32x32x16_bf16 v[80:95], v[182:185], v[194:197], v[80:95]
	ds_read_b128 v[182:185], v139 offset:8192
	s_waitcnt lgkmcnt(3)
	v_mfma_f32_32x32x16_bf16 v[96:111], v[186:189], v[190:193], v[96:111]
	v_mfma_f32_32x32x16_bf16 v[112:127], v[186:189], v[194:197], v[112:127]
	ds_read_b128 v[186:189], v139 offset:12288
	s_waitcnt lgkmcnt(3)
	v_mfma_f32_32x32x16_bf16 v[0:15], v[170:173], v[198:201], v[0:15]
	v_mfma_f32_32x32x16_bf16 v[16:31], v[170:173], v[202:205], v[16:31]
	ds_read_b128 v[170:173], v140
	s_waitcnt lgkmcnt(3)
	v_mfma_f32_32x32x16_bf16 v[32:47], v[174:177], v[198:201], v[32:47]
	v_mfma_f32_32x32x16_bf16 v[48:63], v[174:177], v[202:205], v[48:63]
	ds_read_b128 v[174:177], v140 offset:4096
	s_waitcnt lgkmcnt(3)
	v_mfma_f32_32x32x16_bf16 v[64:79], v[182:185], v[198:201], v[64:79]
	v_mfma_f32_32x32x16_bf16 v[80:95], v[182:185], v[202:205], v[80:95]
	ds_read_b128 v[182:185], v140 offset:8192
	s_waitcnt lgkmcnt(3)
	v_mfma_f32_32x32x16_bf16 v[96:111], v[186:189], v[198:201], v[96:111]
	v_mfma_f32_32x32x16_bf16 v[112:127], v[186:189], v[202:205], v[112:127]
	ds_read_b128 v[186:189], v140 offset:12288
	s_waitcnt lgkmcnt(3)
	v_mfma_f32_32x32x16_bf16 v[0:15], v[170:173], v[206:209], v[0:15]
	v_mfma_f32_32x32x16_bf16 v[16:31], v[170:173], v[222:225], v[16:31]
	ds_read_b128 v[170:173], v141
	s_waitcnt lgkmcnt(3)
	v_mfma_f32_32x32x16_bf16 v[32:47], v[174:177], v[206:209], v[32:47]
	v_mfma_f32_32x32x16_bf16 v[48:63], v[174:177], v[222:225], v[48:63]
	ds_read_b128 v[174:177], v141 offset:4096
	s_waitcnt lgkmcnt(3)
	v_mfma_f32_32x32x16_bf16 v[64:79], v[182:185], v[206:209], v[64:79]
	v_mfma_f32_32x32x16_bf16 v[80:95], v[182:185], v[222:225], v[80:95]
	ds_read_b128 v[182:185], v141 offset:8192
	s_waitcnt lgkmcnt(3)
	v_mfma_f32_32x32x16_bf16 v[96:111], v[186:189], v[206:209], v[96:111]
	v_mfma_f32_32x32x16_bf16 v[112:127], v[186:189], v[222:225], v[112:127]
	ds_read_b128 v[186:189], v141 offset:12288
	s_waitcnt lgkmcnt(3)
	v_mfma_f32_32x32x16_bf16 v[0:15], v[170:173], v[226:229], v[0:15]
	v_mfma_f32_32x32x16_bf16 v[16:31], v[170:173], v[230:233], v[16:31]
	s_waitcnt lgkmcnt(2)
	v_mfma_f32_32x32x16_bf16 v[32:47], v[174:177], v[226:229], v[32:47]
	v_mfma_f32_32x32x16_bf16 v[48:63], v[174:177], v[230:233], v[48:63]
	s_waitcnt lgkmcnt(1)
	v_mfma_f32_32x32x16_bf16 v[64:79], v[182:185], v[226:229], v[64:79]
	v_mfma_f32_32x32x16_bf16 v[80:95], v[182:185], v[230:233], v[80:95]
	s_waitcnt lgkmcnt(0)
	v_mfma_f32_32x32x16_bf16 v[96:111], v[186:189], v[226:229], v[96:111]
	v_mfma_f32_32x32x16_bf16 v[112:127], v[186:189], v[230:233], v[112:127]
	v_xor_b32_e32 v138, 0x8000, v138
	v_xor_b32_e32 v139, 0x8000, v139
	v_xor_b32_e32 v140, 0x8000, v140
	v_xor_b32_e32 v141, 0x8000, v141
	s_xor_b32 s15, s15, 0x8000
	s_add_i32 s14, s14, 1
	s_cmp_eq_u32 s14, 16
	s_cbranch_scc0 .Lg_ph5_top
	v_mov_b32_e32 v175, 0x12000
	v_mov_b32_e32 v176, s52
	v_mov_b32_e32 v177, s53
	ds_write_b64 v175, v[176:177]
	s_waitcnt vmcnt(0)
	v_mov_b32_e32 v130, v180
	v_add_u32_e32 v201, 0x400, v153
	v_add_u32_e32 v200, 0x1000, v153
	v_add_u32_e32 v199, 0x1400, v153
	v_add_u32_e32 v198, 0x2000, v153
	v_add_u32_e32 v192, 0x2400, v153
	v_add_u32_e32 v193, 0x3000, v153
	v_add_u32_e32 v194, 0x3200, v153
	v_add_u32_e32 v195, 0x3400, v153
	v_add_u32_e32 v196, 0x3600, v153
	v_add_u32_e32 v197, 0x4000, v153
	v_add_u32_e32 v189, 0x4400, v153
	v_add_u32_e32 v190, 0x4800, v153
	v_add_u32_e32 v191, 0x5000, v153
	v_add_u32_e32 v186, 0x5400, v153
	v_add_u32_e32 v187, 0x5800, v153
	v_add_u32_e32 v188, 0x6000, v153
	v_add_u32_e32 v179, 0x6400, v153
	v_add_u32_e32 v181, 0x6800, v153
	v_add_u32_e32 v182, 0x7200, v153
	v_add_u32_e32 v183, 0x7400, v153
	v_add_u32_e32 v184, 0x7600, v153
	v_add_u32_e32 v185, 0x7800, v153
	v_add_u32_e32 v178, 0x8400, v153
	v_add_u32_e32 v177, 0x8800, v153
	v_add_u32_e32 v176, 0x9400, v153
	v_add_u32_e32 v175, 0x9800, v153
	v_add_u32_e32 v174, 0xa400, v153
	v_add_u32_e32 v147, 0xa800, v153
	v_add_u32_e32 v169, 0xb400, v153
	v_add_u32_e32 v170, 0xb600, v153
	v_add_u32_e32 v171, 0xb800, v153
	v_add_u32_e32 v172, 0xba00, v153
	s_waitcnt vmcnt(0)
	s_barrier
	s_and_saveexec_b64 s[14:15], s[6:7]
	s_cbranch_execz .LBB0_605
	v_add_u32_e32 v136, 0xc400, v153
	ds_write2_b32 v153, v0, v16 offset1:32
	ds_write2_b32 v153, v1, v17 offset0:132 offset1:164
	ds_write2_b32 v201, v2, v18 offset0:8 offset1:40
	ds_write2_b32 v201, v3, v19 offset0:140 offset1:172
	ds_write2_b32 v200, v4, v20 offset0:32 offset1:64
	ds_write2_b32 v200, v5, v21 offset0:164 offset1:196
	ds_write2_b32 v199, v6, v22 offset0:40 offset1:72
	ds_write2_b32 v199, v7, v23 offset0:172 offset1:204
	ds_write2_b32 v198, v8, v24 offset0:64 offset1:96
	ds_write2_b32 v198, v9, v25 offset0:196 offset1:228
	ds_write2_b32 v192, v10, v26 offset0:72 offset1:104
	ds_write2_b32 v192, v11, v27 offset0:204 offset1:236
	ds_write2_b32 v193, v12, v28 offset0:96 offset1:128
	ds_write2_b32 v194, v13, v29 offset0:100 offset1:132
	ds_write2_b32 v195, v14, v30 offset0:104 offset1:136
	ds_write2_b32 v196, v15, v31 offset0:108 offset1:140
	ds_write2_b32 v197, v32, v48 offset0:128 offset1:160
	ds_write2_b32 v189, v33, v49 offset0:4 offset1:36
	ds_write2_b32 v189, v34, v50 offset0:136 offset1:168
	ds_write2_b32 v190, v35, v51 offset0:12 offset1:44
	ds_write2_b32 v191, v36, v52 offset0:160 offset1:192
	ds_write2_b32 v186, v37, v53 offset0:36 offset1:68
	ds_write2_b32 v186, v38, v54 offset0:168 offset1:200
	ds_write2_b32 v187, v39, v55 offset0:44 offset1:76
	ds_write2_b32 v188, v40, v56 offset0:192 offset1:224
	ds_write2_b32 v179, v41, v57 offset0:68 offset1:100
	ds_write2_b32 v179, v42, v58 offset0:200 offset1:232
	ds_write2_b32 v181, v43, v59 offset0:76 offset1:108
	ds_write2_b32 v182, v44, v60 offset0:96 offset1:128
	ds_write2_b32 v183, v45, v61 offset0:100 offset1:132
	ds_write2_b32 v184, v46, v62 offset0:104 offset1:136
	ds_write2_b32 v185, v47, v63 offset0:108 offset1:140
	ds_write2_b32 v178, v64, v80 offset1:32
	ds_write2_b32 v178, v65, v81 offset0:132 offset1:164
	ds_write2_b32 v177, v66, v82 offset0:8 offset1:40
	ds_write2_b32 v177, v67, v83 offset0:140 offset1:172
	ds_write2_b32 v176, v68, v84 offset0:32 offset1:64
	ds_write2_b32 v176, v69, v85 offset0:164 offset1:196
	ds_write2_b32 v175, v70, v86 offset0:40 offset1:72
	ds_write2_b32 v175, v71, v87 offset0:172 offset1:204
	ds_write2_b32 v174, v72, v88 offset0:64 offset1:96
	ds_write2_b32 v174, v73, v89 offset0:196 offset1:228
	ds_write2_b32 v147, v74, v90 offset0:72 offset1:104
	ds_write2_b32 v147, v75, v91 offset0:204 offset1:236
	ds_write2_b32 v169, v76, v92 offset0:96 offset1:128
	ds_write2_b32 v170, v77, v93 offset0:100 offset1:132
	ds_write2_b32 v171, v78, v94 offset0:104 offset1:136
	ds_write2_b32 v172, v79, v95 offset0:108 offset1:140
	ds_write2_b32 v136, v96, v112 offset0:128 offset1:160
	v_add_u32_e32 v136, 0xc800, v153
	ds_write2_b32 v136, v97, v113 offset0:4 offset1:36
	ds_write2_b32 v136, v98, v114 offset0:136 offset1:168
	v_add_u32_e32 v136, 0xcc00, v153
	ds_write2_b32 v136, v99, v115 offset0:12 offset1:44
	v_add_u32_e32 v136, 0xd400, v153
	ds_write2_b32 v136, v100, v116 offset0:160 offset1:192
	v_add_u32_e32 v136, 0xd800, v153
	ds_write2_b32 v136, v101, v117 offset0:36 offset1:68
	ds_write2_b32 v136, v102, v118 offset0:168 offset1:200
	v_add_u32_e32 v136, 0xdc00, v153
	ds_write2_b32 v136, v103, v119 offset0:44 offset1:76
	v_add_u32_e32 v136, 0xe400, v153
	ds_write2_b32 v136, v104, v120 offset0:192 offset1:224
	v_add_u32_e32 v136, 0xe800, v153
	ds_write2_b32 v136, v105, v121 offset0:68 offset1:100
	ds_write2_b32 v136, v106, v122 offset0:200 offset1:232
	v_add_u32_e32 v136, 0xec00, v153
	ds_write2_b32 v136, v107, v123 offset0:76 offset1:108
	v_add_u32_e32 v136, 0xf600, v153
	ds_write2_b32 v136, v108, v124 offset0:96 offset1:128
	v_add_u32_e32 v136, 0xf800, v153
	ds_write2_b32 v136, v109, v125 offset0:100 offset1:132
	v_add_u32_e32 v136, 0xfa00, v153
	ds_write2_b32 v136, v110, v126 offset0:104 offset1:136
	v_add_u32_e32 v136, 0xfc00, v153
	ds_write2_b32 v136, v111, v127 offset0:108 offset1:140

.LBB0_1174:
	s_and_b32 s4, s31, 0xff
	s_mulk_i32 s4, 0xab
	s_lshr_b32 s4, s4, 12
	s_add_i32 s24, s34, s4
	s_lshl_b32 s44, s24, 18
	v_or_b32_e32 v0, s44, v129
	v_or_b32_e32 v1, v0, v128
	s_mul_i32 s4, s4, 24
	v_lshlrev_b32_e32 v130, 1, v1
	v_add_lshl_u32 v1, v0, v128, 1
	s_sub_i32 s4, s31, s4
	v_add_u32_e32 v0, 0x20000, v1
	v_add_u32_e32 v2, 0x40000, v1
	v_add_u32_e32 v4, 0x60000, v1
	v_mov_b32_e32 v1, v131
	v_mov_b32_e32 v3, v131
	v_mov_b32_e32 v5, v131
	s_and_b32 s43, s4, 0xff
	v_lshl_add_u64 v[136:137], s[2:3], 0, v[130:131]
	v_lshl_add_u64 v[138:139], s[2:3], 0, v[0:1]
	v_lshl_add_u64 v[140:141], s[2:3], 0, v[2:3]
	v_lshl_add_u64 v[142:143], s[2:3], 0, v[4:5]
	s_cmp_gt_u32 s43, 15
	v_lshl_add_u64 v[150:151], v[136:137], 0, 64
	s_mov_b64 s[24:25], -1
	v_lshl_add_u64 v[148:149], v[138:139], 0, 64
	v_lshl_add_u64 v[146:147], v[140:141], 0, 64
	v_lshl_add_u64 v[144:145], v[142:143], 0, 64
	s_cbranch_scc0 .LBB0_1182
	s_lshl_b32 s4, s43, 7
	s_add_i32 s24, s4, 0xfffff800
	s_mov_b32 s25, s5
	v_readfirstlane_b32 s4, v160
	s_lshl_b64 s[26:27], s[24:25], 11
	s_mov_b32 m0, s4
	v_readfirstlane_b32 s4, v168
	s_add_u32 s26, s28, s26
	s_waitcnt vmcnt(0)
	s_barrier
	s_nop 0
	s_mov_b32 m0, s4
	v_readfirstlane_b32 s4, v169
	s_addc_u32 s27, s29, s27
	v_mov_b32_e32 v135, v131
	s_nop 0
	s_mov_b32 m0, s4
	v_readfirstlane_b32 s4, v170
	v_lshl_add_u64 v[0:1], s[26:27], 0, v[134:135]
	v_mov_b32_e32 v133, v131
	s_nop 0
	s_mov_b32 m0, s4
	v_readfirstlane_b32 s4, v171
	v_lshl_add_u64 v[152:153], v[0:1], 0, v[132:133]
	s_nop 0
	s_mov_b32 m0, s4
	v_readfirstlane_b32 s4, v172
	v_lshl_add_u64 v[154:155], v[152:153], 0, s[10:11]
	s_nop 0
	s_mov_b32 m0, s4
	v_readfirstlane_b32 s4, v173
	s_nop 0
	s_mov_b32 m0, s4
	v_readfirstlane_b32 s4, v174
	s_nop 0
	s_mov_b32 m0, s4
	v_readfirstlane_b32 s4, v175
	s_nop 0
	s_mov_b32 m0, s4
	v_readfirstlane_b32 s4, v176
	s_nop 0
	s_mov_b32 m0, s4
	v_readfirstlane_b32 s4, v177
	s_nop 0
	v_lshl_add_u64 v[0:1], v[152:153], 0, 64
	s_mov_b32 m0, s4
	v_readfirstlane_b32 s4, v178
	s_nop 0
	v_lshl_add_u64 v[0:1], v[152:153], 0, s[12:13]
	s_mov_b32 m0, s4
	s_mov_b32 s27, 2
	s_nop 0
	v_mov_b32_e32 v0, 0
	s_mov_b32 s26, 0
	s_mov_b32 s45, 0
	v_mov_b32_e32 v1, v0
	v_mov_b32_e32 v2, v0
	v_mov_b32_e32 v3, v0
	v_mov_b32_e32 v4, v0
	v_mov_b32_e32 v5, v0
	v_mov_b32_e32 v6, v0
	v_mov_b32_e32 v7, v0
	v_mov_b32_e32 v8, v0
	v_mov_b32_e32 v9, v0
	v_mov_b32_e32 v10, v0
	v_mov_b32_e32 v11, v0
	v_mov_b32_e32 v12, v0
	v_mov_b32_e32 v13, v0
	v_mov_b32_e32 v14, v0
	v_mov_b32_e32 v15, v0
	v_mov_b32_e32 v48, v0
	v_mov_b32_e32 v49, v0
	v_mov_b32_e32 v50, v0
	v_mov_b32_e32 v51, v0
	v_mov_b32_e32 v52, v0
	v_mov_b32_e32 v53, v0
	v_mov_b32_e32 v54, v0
	v_mov_b32_e32 v55, v0
	v_mov_b32_e32 v56, v0
	v_mov_b32_e32 v57, v0
	v_mov_b32_e32 v58, v0
	v_mov_b32_e32 v59, v0
	v_mov_b32_e32 v60, v0
	v_mov_b32_e32 v61, v0
	v_mov_b32_e32 v62, v0
	v_mov_b32_e32 v63, v0
	v_mov_b32_e32 v16, v0
	v_mov_b32_e32 v17, v0
	v_mov_b32_e32 v18, v0
	v_mov_b32_e32 v19, v0
	v_mov_b32_e32 v20, v0
	v_mov_b32_e32 v21, v0
	v_mov_b32_e32 v22, v0
	v_mov_b32_e32 v23, v0
	v_mov_b32_e32 v24, v0
	v_mov_b32_e32 v25, v0
	v_mov_b32_e32 v26, v0
	v_mov_b32_e32 v27, v0
	v_mov_b32_e32 v28, v0
	v_mov_b32_e32 v29, v0
	v_mov_b32_e32 v30, v0
	v_mov_b32_e32 v31, v0
	v_mov_b32_e32 v64, v0
	v_mov_b32_e32 v65, v0
	v_mov_b32_e32 v66, v0
	v_mov_b32_e32 v67, v0
	v_mov_b32_e32 v68, v0
	v_mov_b32_e32 v69, v0
	v_mov_b32_e32 v70, v0
	v_mov_b32_e32 v71, v0
	v_mov_b32_e32 v72, v0
	v_mov_b32_e32 v73, v0
	v_mov_b32_e32 v74, v0
	v_mov_b32_e32 v75, v0
	v_mov_b32_e32 v76, v0
	v_mov_b32_e32 v77, v0
	v_mov_b32_e32 v78, v0
	v_mov_b32_e32 v79, v0
	v_mov_b32_e32 v32, v0
	v_mov_b32_e32 v33, v0
	v_mov_b32_e32 v34, v0
	v_mov_b32_e32 v35, v0
	v_mov_b32_e32 v36, v0
	v_mov_b32_e32 v37, v0
	v_mov_b32_e32 v38, v0
	v_mov_b32_e32 v39, v0
	v_mov_b32_e32 v40, v0
	v_mov_b32_e32 v41, v0
	v_mov_b32_e32 v42, v0
	v_mov_b32_e32 v43, v0
	v_mov_b32_e32 v44, v0
	v_mov_b32_e32 v45, v0
	v_mov_b32_e32 v46, v0
	v_mov_b32_e32 v47, v0
	v_mov_b32_e32 v112, v0
	v_mov_b32_e32 v113, v0
	v_mov_b32_e32 v114, v0
	v_mov_b32_e32 v115, v0
	v_mov_b32_e32 v116, v0
	v_mov_b32_e32 v117, v0
	v_mov_b32_e32 v118, v0
	v_mov_b32_e32 v119, v0
	v_mov_b32_e32 v120, v0
	v_mov_b32_e32 v121, v0
	v_mov_b32_e32 v122, v0
	v_mov_b32_e32 v123, v0
	v_mov_b32_e32 v124, v0
	v_mov_b32_e32 v125, v0
	v_mov_b32_e32 v126, v0
	v_mov_b32_e32 v127, v0
	v_mov_b32_e32 v80, v0
	v_mov_b32_e32 v81, v0
	v_mov_b32_e32 v82, v0
	v_mov_b32_e32 v83, v0
	v_mov_b32_e32 v84, v0
	v_mov_b32_e32 v85, v0
	v_mov_b32_e32 v86, v0
	v_mov_b32_e32 v87, v0
	v_mov_b32_e32 v88, v0
	v_mov_b32_e32 v89, v0
	v_mov_b32_e32 v90, v0
	v_mov_b32_e32 v91, v0
	v_mov_b32_e32 v92, v0
	v_mov_b32_e32 v93, v0
	v_mov_b32_e32 v94, v0
	v_mov_b32_e32 v95, v0
	v_mov_b32_e32 v96, v0
	v_mov_b32_e32 v97, v0
	v_mov_b32_e32 v98, v0
	v_mov_b32_e32 v99, v0
	v_mov_b32_e32 v100, v0
	v_mov_b32_e32 v101, v0
	v_mov_b32_e32 v102, v0
	v_mov_b32_e32 v103, v0
	v_mov_b32_e32 v104, v0
	v_mov_b32_e32 v105, v0
	v_mov_b32_e32 v106, v0
	v_mov_b32_e32 v107, v0
	v_mov_b32_e32 v108, v0
	v_mov_b32_e32 v109, v0
	v_mov_b32_e32 v110, v0
	v_mov_b32_e32 v111, v0
	s_mov_b64 s[54:55], 0x80
	v_lshrrev_b32_e32 v182, 6, v180
	v_lshlrev_b32_e32 v192, 11, v182
	v_mov_b32_e32 v183, 0x12000
	ds_read_b64 v[184:185], v183
	v_and_b32_e32 v156, 63, v180
	v_readfirstlane_b32 s53, v192
	v_lshrrev_b32_e32 v157, 5, v156
	v_bfe_u32 v158, v156, 1, 3
	v_xor_b32_e32 v158, v157, v158
	v_and_b32_e32 v159, 31, v156
	v_lshlrev_b32_e32 v159, 7, v159
	v_lshrrev_b32_e32 v159, 3, v156
	v_lshlrev_b32_e32 v192, 4, v159
	v_add_u32_e32 v193, 0x80, v192
	v_and_b32_e32 v159, 7, v156
	v_lshrrev_b32_e32 v157, 4, v156
	v_xor_b32_e32 v157, v159, v157
	v_lshrrev_b32_e32 v159, 5, v156
	v_sub_u32_e32 v194, v157, v159
	v_xor_b32_e32 v157, 4, v157
	v_add_u32_e32 v159, 2, v159
	v_sub_u32_e32 v196, v157, v159
	v_lshlrev_b32_e32 v194, 4, v194
	v_ashrrev_i32_e32 v195, 31, v194
	v_lshlrev_b32_e32 v196, 4, v196
	v_ashrrev_i32_e32 v197, 31, v196
	ds_bpermute_b32 v244, v192, v152
	ds_bpermute_b32 v245, v192, v153
	ds_bpermute_b32 v246, v193, v152
	ds_bpermute_b32 v247, v193, v153
	ds_bpermute_b32 v248, v192, v154
	ds_bpermute_b32 v249, v192, v155
	ds_bpermute_b32 v250, v193, v154
	ds_bpermute_b32 v251, v193, v155
	s_waitcnt lgkmcnt(0)
	ds_bpermute_b32 v186, v192, v136
	ds_bpermute_b32 v187, v192, v137
	ds_bpermute_b32 v234, v193, v136
	ds_bpermute_b32 v235, v193, v137
	ds_bpermute_b32 v236, v192, v138
	ds_bpermute_b32 v237, v192, v139
	ds_bpermute_b32 v238, v193, v138
	ds_bpermute_b32 v239, v193, v139
	ds_bpermute_b32 v240, v192, v140
	ds_bpermute_b32 v241, v192, v141
	ds_bpermute_b32 v242, v193, v140
	ds_bpermute_b32 v243, v193, v141
	ds_bpermute_b32 v152, v192, v142
	ds_bpermute_b32 v153, v192, v143
	ds_bpermute_b32 v154, v193, v142
	ds_bpermute_b32 v155, v193, v143
	s_waitcnt lgkmcnt(0)
	v_readfirstlane_b32 s56, v184
	v_readfirstlane_b32 s57, v185
	v_and_b32_e32 v159, 31, v156
	v_lshlrev_b32_e32 v159, 7, v159
	v_lshrrev_b32_e32 v157, 1, v182
	v_lshl_add_u32 v136, v157, 14, v159
	v_and_b32_e32 v157, 1, v182
	v_lshl_add_u32 v140, v157, 13, v159
	v_add_u32_e32 v140, 0x10000, v140
	v_xor_b32_e32 v159, 6, v158
	v_lshl_add_u32 v139, v159, 4, v136
	v_lshl_add_u32 v143, v159, 4, v140
	v_xor_b32_e32 v159, 4, v158
	v_lshl_add_u32 v138, v159, 4, v136
	v_lshl_add_u32 v142, v159, 4, v140
	v_xor_b32_e32 v159, 2, v158
	v_lshl_add_u32 v137, v159, 4, v136
	v_lshl_add_u32 v141, v159, 4, v140
	v_xor_b32_e32 v159, 0, v158
	v_lshl_add_u32 v136, v159, 4, v136
	v_lshl_add_u32 v140, v159, 4, v140
	v_lshl_add_u64 v[186:187], v[186:187], 0, v[194:195]
	v_lshl_add_u64 v[234:235], v[234:235], 0, v[196:197]
	v_lshl_add_u64 v[236:237], v[236:237], 0, v[194:195]
	v_lshl_add_u64 v[238:239], v[238:239], 0, v[196:197]
	v_lshl_add_u64 v[240:241], v[240:241], 0, v[194:195]
	v_lshl_add_u64 v[242:243], v[242:243], 0, v[196:197]
	v_lshl_add_u64 v[152:153], v[152:153], 0, v[194:195]
	v_lshl_add_u64 v[154:155], v[154:155], 0, v[196:197]
	v_lshl_add_u64 v[244:245], v[244:245], 0, v[194:195]
	v_lshl_add_u64 v[246:247], v[246:247], 0, v[196:197]
	v_lshl_add_u64 v[248:249], v[248:249], 0, v[194:195]
	v_lshl_add_u64 v[250:251], v[250:251], 0, v[196:197]
	s_mov_b32 s58, s53
	s_add_i32 m0, s58, 0x0
	s_nop 0
	global_load_lds_dwordx4 v[186:187], off
	s_add_i32 m0, s58, 0x400
	v_lshl_add_u64 v[186:187], v[186:187], 0, s[54:55]
	global_load_lds_dwordx4 v[234:235], off
	s_add_i32 m0, s58, 0x2000
	v_lshl_add_u64 v[234:235], v[234:235], 0, s[54:55]
	global_load_lds_dwordx4 v[236:237], off
	s_add_i32 m0, s58, 0x2400
	v_lshl_add_u64 v[236:237], v[236:237], 0, s[54:55]
	global_load_lds_dwordx4 v[238:239], off
	s_add_i32 m0, s58, 0x4000
	v_lshl_add_u64 v[238:239], v[238:239], 0, s[54:55]
	global_load_lds_dwordx4 v[240:241], off
	s_add_i32 m0, s58, 0x4400
	v_lshl_add_u64 v[240:241], v[240:241], 0, s[54:55]
	global_load_lds_dwordx4 v[242:243], off
	s_add_i32 m0, s58, 0x6000
	v_lshl_add_u64 v[242:243], v[242:243], 0, s[54:55]
	global_load_lds_dwordx4 v[152:153], off
	s_add_i32 m0, s58, 0x6400
	v_lshl_add_u64 v[152:153], v[152:153], 0, s[54:55]
	global_load_lds_dwordx4 v[154:155], off
	v_lshl_add_u64 v[154:155], v[154:155], 0, s[54:55]
	s_add_i32 s58, s53, 0x10000
	s_add_i32 m0, s58, 0x0
	s_nop 0
	global_load_lds_dwordx4 v[244:245], off
	s_add_i32 m0, s58, 0x400
	v_lshl_add_u64 v[244:245], v[244:245], 0, s[54:55]
	global_load_lds_dwordx4 v[246:247], off
	s_add_i32 m0, s58, 0x2000
	v_lshl_add_u64 v[246:247], v[246:247], 0, s[54:55]
	global_load_lds_dwordx4 v[248:249], off
	s_add_i32 m0, s58, 0x2400
	v_lshl_add_u64 v[248:249], v[248:249], 0, s[54:55]
	global_load_lds_dwordx4 v[250:251], off
	v_lshl_add_u64 v[250:251], v[250:251], 0, s[54:55]
	s_mov_b32 s26, 0
	s_mov_b32 s27, 0
.Lg_ph11a_top:
	s_waitcnt vmcnt(0)
	s_waitcnt lgkmcnt(0)
	s_barrier
	s_cmp_eq_u32 s26, 15
	s_cbranch_scc1 .Lg_ph11a_noA
	s_xor_b32 s58, s27, 0x8000
	s_add_i32 s58, s58, s53
	s_add_i32 m0, s58, 0x0
	s_nop 0
	global_load_lds_dwordx4 v[186:187], off
	s_add_i32 m0, s58, 0x400
	v_lshl_add_u64 v[186:187], v[186:187], 0, s[54:55]
	global_load_lds_dwordx4 v[234:235], off
	s_add_i32 m0, s58, 0x2000
	v_lshl_add_u64 v[234:235], v[234:235], 0, s[54:55]
	global_load_lds_dwordx4 v[236:237], off
	s_add_i32 m0, s58, 0x2400
	v_lshl_add_u64 v[236:237], v[236:237], 0, s[54:55]
	global_load_lds_dwordx4 v[238:239], off
	s_add_i32 m0, s58, 0x4000
	v_lshl_add_u64 v[238:239], v[238:239], 0, s[54:55]
	global_load_lds_dwordx4 v[240:241], off
	s_add_i32 m0, s58, 0x4400
	v_lshl_add_u64 v[240:241], v[240:241], 0, s[54:55]
	global_load_lds_dwordx4 v[242:243], off
	s_add_i32 m0, s58, 0x6000
	v_lshl_add_u64 v[242:243], v[242:243], 0, s[54:55]
	global_load_lds_dwordx4 v[152:153], off
	s_add_i32 m0, s58, 0x6400
	v_lshl_add_u64 v[152:153], v[152:153], 0, s[54:55]
	global_load_lds_dwordx4 v[154:155], off
	v_lshl_add_u64 v[154:155], v[154:155], 0, s[54:55]
.Lg_ph11a_noA:
	ds_read_b128 v[198:201], v140
	ds_read_b128 v[202:205], v140 offset:4096
	ds_read_b128 v[206:209], v141
	ds_read_b128 v[214:217], v141 offset:4096
	ds_read_b128 v[218:221], v142
	ds_read_b128 v[222:225], v142 offset:4096
	ds_read_b128 v[226:229], v143
	ds_read_b128 v[230:233], v143 offset:4096
	ds_read_b128 v[156:159], v136
	ds_read_b128 v[182:185], v136 offset:4096
	ds_read_b128 v[190:193], v136 offset:8192
	ds_read_b128 v[194:197], v136 offset:12288
	s_waitcnt lgkmcnt(4)
	s_barrier
	s_cmp_eq_u32 s26, 15
	s_cbranch_scc1 .Lg_ph11a_noB
	s_add_i32 s58, s53, 0x10000
	s_add_i32 m0, s58, 0x0
	s_nop 0
	global_load_lds_dwordx4 v[244:245], off
	s_add_i32 m0, s58, 0x400
	v_lshl_add_u64 v[244:245], v[244:245], 0, s[54:55]
	global_load_lds_dwordx4 v[246:247], off
	s_add_i32 m0, s58, 0x2000
	v_lshl_add_u64 v[246:247], v[246:247], 0, s[54:55]
	global_load_lds_dwordx4 v[248:249], off
	s_add_i32 m0, s58, 0x2400
	v_lshl_add_u64 v[248:249], v[248:249], 0, s[54:55]
	global_load_lds_dwordx4 v[250:251], off
	v_lshl_add_u64 v[250:251], v[250:251], 0, s[54:55]
.Lg_ph11a_noB:
	s_waitcnt lgkmcnt(3)
	v_mfma_f32_32x32x16_bf16 v[0:15], v[156:159], v[198:201], v[0:15]
	v_mfma_f32_32x32x16_bf16 v[48:63], v[156:159], v[202:205], v[48:63]
	ds_read_b128 v[156:159], v137
	s_waitcnt lgkmcnt(3)
	v_mfma_f32_32x32x16_bf16 v[16:31], v[182:185], v[198:201], v[16:31]
	v_mfma_f32_32x32x16_bf16 v[64:79], v[182:185], v[202:205], v[64:79]
	ds_read_b128 v[182:185], v137 offset:4096
	s_waitcnt lgkmcnt(3)
	v_mfma_f32_32x32x16_bf16 v[32:47], v[190:193], v[198:201], v[32:47]
	v_mfma_f32_32x32x16_bf16 v[112:127], v[190:193], v[202:205], v[112:127]
	ds_read_b128 v[190:193], v137 offset:8192
	s_waitcnt lgkmcnt(3)
	v_mfma_f32_32x32x16_bf16 v[80:95], v[194:197], v[198:201], v[80:95]
	v_mfma_f32_32x32x16_bf16 v[96:111], v[194:197], v[202:205], v[96:111]
	ds_read_b128 v[194:197], v137 offset:12288
	s_waitcnt lgkmcnt(3)
	v_mfma_f32_32x32x16_bf16 v[0:15], v[156:159], v[206:209], v[0:15]
	v_mfma_f32_32x32x16_bf16 v[48:63], v[156:159], v[214:217], v[48:63]
	ds_read_b128 v[156:159], v138
	s_waitcnt lgkmcnt(3)
	v_mfma_f32_32x32x16_bf16 v[16:31], v[182:185], v[206:209], v[16:31]
	v_mfma_f32_32x32x16_bf16 v[64:79], v[182:185], v[214:217], v[64:79]
	ds_read_b128 v[182:185], v138 offset:4096
	s_waitcnt lgkmcnt(3)
	v_mfma_f32_32x32x16_bf16 v[32:47], v[190:193], v[206:209], v[32:47]
	v_mfma_f32_32x32x16_bf16 v[112:127], v[190:193], v[214:217], v[112:127]
	ds_read_b128 v[190:193], v138 offset:8192
	s_waitcnt lgkmcnt(3)
	v_mfma_f32_32x32x16_bf16 v[80:95], v[194:197], v[206:209], v[80:95]
	v_mfma_f32_32x32x16_bf16 v[96:111], v[194:197], v[214:217], v[96:111]
	ds_read_b128 v[194:197], v138 offset:12288
	s_waitcnt lgkmcnt(3)
	v_mfma_f32_32x32x16_bf16 v[0:15], v[156:159], v[218:221], v[0:15]
	v_mfma_f32_32x32x16_bf16 v[48:63], v[156:159], v[222:225], v[48:63]
	ds_read_b128 v[156:159], v139
	s_waitcnt lgkmcnt(3)
	v_mfma_f32_32x32x16_bf16 v[16:31], v[182:185], v[218:221], v[16:31]
	v_mfma_f32_32x32x16_bf16 v[64:79], v[182:185], v[222:225], v[64:79]
	ds_read_b128 v[182:185], v139 offset:4096
	s_waitcnt lgkmcnt(3)
	v_mfma_f32_32x32x16_bf16 v[32:47], v[190:193], v[218:221], v[32:47]
	v_mfma_f32_32x32x16_bf16 v[112:127], v[190:193], v[222:225], v[112:127]
	ds_read_b128 v[190:193], v139 offset:8192
	s_waitcnt lgkmcnt(3)
	v_mfma_f32_32x32x16_bf16 v[80:95], v[194:197], v[218:221], v[80:95]
	v_mfma_f32_32x32x16_bf16 v[96:111], v[194:197], v[222:225], v[96:111]
	ds_read_b128 v[194:197], v139 offset:12288
	s_waitcnt lgkmcnt(3)
	v_mfma_f32_32x32x16_bf16 v[0:15], v[156:159], v[226:229], v[0:15]
	v_mfma_f32_32x32x16_bf16 v[48:63], v[156:159], v[230:233], v[48:63]
	s_waitcnt lgkmcnt(2)
	v_mfma_f32_32x32x16_bf16 v[16:31], v[182:185], v[226:229], v[16:31]
	v_mfma_f32_32x32x16_bf16 v[64:79], v[182:185], v[230:233], v[64:79]
	s_waitcnt lgkmcnt(1)
	v_mfma_f32_32x32x16_bf16 v[32:47], v[190:193], v[226:229], v[32:47]
	v_mfma_f32_32x32x16_bf16 v[112:127], v[190:193], v[230:233], v[112:127]
	s_waitcnt lgkmcnt(0)
	v_mfma_f32_32x32x16_bf16 v[80:95], v[194:197], v[226:229], v[80:95]
	v_mfma_f32_32x32x16_bf16 v[96:111], v[194:197], v[230:233], v[96:111]
	v_xor_b32_e32 v136, 0x8000, v136
	v_xor_b32_e32 v137, 0x8000, v137
	v_xor_b32_e32 v138, 0x8000, v138
	v_xor_b32_e32 v139, 0x8000, v139
	s_xor_b32 s27, s27, 0x8000
	s_add_i32 s26, s26, 1
	s_cmp_eq_u32 s26, 16
	s_cbranch_scc0 .Lg_ph11a_top
	v_mov_b32_e32 v183, 0x12000
	v_mov_b32_e32 v184, s56
	v_mov_b32_e32 v185, s57
	ds_write_b64 v183, v[184:185]
	s_waitcnt vmcnt(0)
	v_mov_b32_e32 v130, v180
	s_waitcnt vmcnt(0)
	s_barrier
	s_and_saveexec_b64 s[26:27], s[6:7]
	s_cbranch_execz .LBB0_1179
	v_add_u32_e32 v133, 0x400, v166
	ds_write2_b32 v166, v0, v48 offset1:32
	ds_write2_b32 v166, v1, v49 offset0:132 offset1:164
	ds_write2_b32 v133, v2, v50 offset0:8 offset1:40
	ds_write2_b32 v133, v3, v51 offset0:140 offset1:172
	v_add_u32_e32 v133, 0x1000, v166
	ds_write2_b32 v133, v4, v52 offset0:32 offset1:64
	ds_write2_b32 v133, v5, v53 offset0:164 offset1:196
	v_add_u32_e32 v133, 0x1400, v166
	ds_write2_b32 v133, v6, v54 offset0:40 offset1:72
	ds_write2_b32 v133, v7, v55 offset0:172 offset1:204
	v_add_u32_e32 v133, 0x2000, v166
	ds_write2_b32 v133, v8, v56 offset0:64 offset1:96
	ds_write2_b32 v133, v9, v57 offset0:196 offset1:228
	v_add_u32_e32 v133, 0x2400, v166
	ds_write2_b32 v133, v10, v58 offset0:72 offset1:104
	ds_write2_b32 v133, v11, v59 offset0:204 offset1:236
	v_add_u32_e32 v133, 0x3000, v166
	ds_write2_b32 v133, v12, v60 offset0:96 offset1:128
	v_add_u32_e32 v133, 0x3200, v166
	ds_write2_b32 v133, v13, v61 offset0:100 offset1:132
	v_add_u32_e32 v133, 0x3400, v166
	ds_write2_b32 v133, v14, v62 offset0:104 offset1:136
	v_add_u32_e32 v133, 0x3600, v166
	ds_write2_b32 v133, v15, v63 offset0:108 offset1:140
	v_add_u32_e32 v133, 0x4000, v166
	ds_write2_b32 v133, v16, v64 offset0:128 offset1:160
	v_add_u32_e32 v133, 0x4400, v166
	ds_write2_b32 v133, v17, v65 offset0:4 offset1:36
	ds_write2_b32 v133, v18, v66 offset0:136 offset1:168
	v_add_u32_e32 v133, 0x4800, v166
	ds_write2_b32 v133, v19, v67 offset0:12 offset1:44
	v_add_u32_e32 v133, 0x5000, v166
	ds_write2_b32 v133, v20, v68 offset0:160 offset1:192
	v_add_u32_e32 v133, 0x5400, v166
	ds_write2_b32 v133, v21, v69 offset0:36 offset1:68
	ds_write2_b32 v133, v22, v70 offset0:168 offset1:200
	v_add_u32_e32 v133, 0x5800, v166
	ds_write2_b32 v133, v23, v71 offset0:44 offset1:76
	v_add_u32_e32 v133, 0x6000, v166
	ds_write2_b32 v133, v24, v72 offset0:192 offset1:224
	v_add_u32_e32 v133, 0x6400, v166
	ds_write2_b32 v133, v25, v73 offset0:68 offset1:100
	ds_write2_b32 v133, v26, v74 offset0:200 offset1:232
	v_add_u32_e32 v133, 0x6800, v166
	ds_write2_b32 v133, v27, v75 offset0:76 offset1:108
	v_add_u32_e32 v133, 0x7200, v166
	ds_write2_b32 v133, v28, v76 offset0:96 offset1:128
	v_add_u32_e32 v133, 0x7400, v166
	ds_write2_b32 v133, v29, v77 offset0:100 offset1:132
	v_add_u32_e32 v133, 0x7600, v166
	ds_write2_b32 v133, v30, v78 offset0:104 offset1:136
	v_add_u32_e32 v133, 0x7800, v166
	ds_write2_b32 v133, v31, v79 offset0:108 offset1:140
	v_add_u32_e32 v133, 0x8400, v166
	ds_write2_b32 v133, v32, v112 offset1:32
	ds_write2_b32 v133, v33, v113 offset0:132 offset1:164
	v_add_u32_e32 v133, 0x8800, v166
	ds_write2_b32 v133, v34, v114 offset0:8 offset1:40
	ds_write2_b32 v133, v35, v115 offset0:140 offset1:172
	v_add_u32_e32 v133, 0x9400, v166
	ds_write2_b32 v133, v36, v116 offset0:32 offset1:64
	ds_write2_b32 v133, v37, v117 offset0:164 offset1:196
	v_add_u32_e32 v133, 0x9800, v166
	ds_write2_b32 v133, v38, v118 offset0:40 offset1:72
	ds_write2_b32 v133, v39, v119 offset0:172 offset1:204
	v_add_u32_e32 v133, 0xa400, v166
	ds_write2_b32 v133, v40, v120 offset0:64 offset1:96
	ds_write2_b32 v133, v41, v121 offset0:196 offset1:228
	v_add_u32_e32 v133, 0xa800, v166
	ds_write2_b32 v133, v42, v122 offset0:72 offset1:104
	ds_write2_b32 v133, v43, v123 offset0:204 offset1:236
	v_add_u32_e32 v133, 0xb400, v166
	ds_write2_b32 v133, v44, v124 offset0:96 offset1:128
	v_add_u32_e32 v133, 0xb600, v166
	ds_write2_b32 v133, v45, v125 offset0:100 offset1:132
	v_add_u32_e32 v133, 0xb800, v166
	ds_write2_b32 v133, v46, v126 offset0:104 offset1:136
	v_add_u32_e32 v133, 0xba00, v166
	ds_write2_b32 v133, v47, v127 offset0:108 offset1:140
	v_add_u32_e32 v133, 0xc400, v166
	ds_write2_b32 v133, v80, v96 offset0:128 offset1:160
	v_add_u32_e32 v133, 0xc800, v166
	ds_write2_b32 v133, v81, v97 offset0:4 offset1:36
	ds_write2_b32 v133, v82, v98 offset0:136 offset1:168
	v_add_u32_e32 v133, 0xcc00, v166
	ds_write2_b32 v133, v83, v99 offset0:12 offset1:44
	v_add_u32_e32 v133, 0xd400, v166
	ds_write2_b32 v133, v84, v100 offset0:160 offset1:192
	v_add_u32_e32 v133, 0xd800, v166
	ds_write2_b32 v133, v85, v101 offset0:36 offset1:68
	ds_write2_b32 v133, v86, v102 offset0:168 offset1:200
	v_add_u32_e32 v133, 0xdc00, v166
	ds_write2_b32 v133, v87, v103 offset0:44 offset1:76
	v_add_u32_e32 v133, 0xe400, v166
	ds_write2_b32 v133, v88, v104 offset0:192 offset1:224
	v_add_u32_e32 v133, 0xe800, v166
	ds_write2_b32 v133, v89, v105 offset0:68 offset1:100
	ds_write2_b32 v133, v90, v106 offset0:200 offset1:232
	v_add_u32_e32 v133, 0xec00, v166
	ds_write2_b32 v133, v91, v107 offset0:76 offset1:108
	v_add_u32_e32 v133, 0xf600, v166
	ds_write2_b32 v133, v92, v108 offset0:96 offset1:128
	v_add_u32_e32 v133, 0xf800, v166
	ds_write2_b32 v133, v93, v109 offset0:100 offset1:132
	v_add_u32_e32 v133, 0xfa00, v166
	ds_write2_b32 v133, v94, v110 offset0:104 offset1:136
	v_add_u32_e32 v133, 0xfc00, v166
	ds_write2_b32 v133, v95, v111 offset0:108 offset1:140

.LBB0_1182:
	s_and_b64 vcc, exec, s[24:25]
	s_cbranch_vccz .LBB0_1173
	s_lshl_b32 s4, s43, 17
	s_add_u32 s24, s28, s4
	v_readfirstlane_b32 s4, v160
	s_mov_b32 m0, s4
	v_readfirstlane_b32 s4, v168
	s_addc_u32 s25, s29, 0
	v_mov_b32_e32 v135, v131
	s_waitcnt vmcnt(0)
	s_barrier
	s_nop 0
	s_mov_b32 m0, s4
	v_readfirstlane_b32 s4, v169
	v_lshl_add_u64 v[0:1], s[24:25], 0, v[134:135]
	v_mov_b32_e32 v133, v131
	s_nop 0
	s_mov_b32 m0, s4
	v_readfirstlane_b32 s4, v170
	v_lshl_add_u64 v[0:1], v[0:1], 0, v[132:133]
	s_nop 0
	s_mov_b32 m0, s4
	v_readfirstlane_b32 s4, v171
	v_lshl_add_u64 v[152:153], v[0:1], 0, s[16:17]
	s_nop 0
	s_mov_b32 m0, s4
	v_readfirstlane_b32 s4, v172
	v_lshl_add_u64 v[154:155], v[0:1], 0, s[18:19]
	s_nop 0
	s_mov_b32 m0, s4
	v_readfirstlane_b32 s4, v173
	s_nop 0
	s_mov_b32 m0, s4
	v_readfirstlane_b32 s4, v174
	s_nop 0
	s_mov_b32 m0, s4
	v_readfirstlane_b32 s4, v175
	s_nop 0
	s_mov_b32 m0, s4
	v_readfirstlane_b32 s4, v176
	s_nop 0
	s_mov_b32 m0, s4
	v_readfirstlane_b32 s4, v177
	s_nop 0
	v_lshl_add_u64 v[2:3], v[0:1], 0, s[20:21]
	s_mov_b32 m0, s4
	v_readfirstlane_b32 s4, v178
	s_nop 0
	v_lshl_add_u64 v[0:1], v[0:1], 0, s[22:23]
	s_mov_b32 m0, s4
	s_mov_b32 s25, 2
	s_nop 0
	v_mov_b32_e32 v0, 0
	s_mov_b32 s24, 0
	s_mov_b32 s26, 0
	v_mov_b32_e32 v1, v0
	v_mov_b32_e32 v2, v0
	v_mov_b32_e32 v3, v0
	v_mov_b32_e32 v4, v0
	v_mov_b32_e32 v5, v0
	v_mov_b32_e32 v6, v0
	v_mov_b32_e32 v7, v0
	v_mov_b32_e32 v8, v0
	v_mov_b32_e32 v9, v0
	v_mov_b32_e32 v10, v0
	v_mov_b32_e32 v11, v0
	v_mov_b32_e32 v12, v0
	v_mov_b32_e32 v13, v0
	v_mov_b32_e32 v14, v0
	v_mov_b32_e32 v15, v0
	v_mov_b32_e32 v16, v0
	v_mov_b32_e32 v17, v0
	v_mov_b32_e32 v18, v0
	v_mov_b32_e32 v19, v0
	v_mov_b32_e32 v20, v0
	v_mov_b32_e32 v21, v0
	v_mov_b32_e32 v22, v0
	v_mov_b32_e32 v23, v0
	v_mov_b32_e32 v24, v0
	v_mov_b32_e32 v25, v0
	v_mov_b32_e32 v26, v0
	v_mov_b32_e32 v27, v0
	v_mov_b32_e32 v28, v0
	v_mov_b32_e32 v29, v0
	v_mov_b32_e32 v30, v0
	v_mov_b32_e32 v31, v0
	v_mov_b32_e32 v32, v0
	v_mov_b32_e32 v33, v0
	v_mov_b32_e32 v34, v0
	v_mov_b32_e32 v35, v0
	v_mov_b32_e32 v36, v0
	v_mov_b32_e32 v37, v0
	v_mov_b32_e32 v38, v0
	v_mov_b32_e32 v39, v0
	v_mov_b32_e32 v40, v0
	v_mov_b32_e32 v41, v0
	v_mov_b32_e32 v42, v0
	v_mov_b32_e32 v43, v0
	v_mov_b32_e32 v44, v0
	v_mov_b32_e32 v45, v0
	v_mov_b32_e32 v46, v0
	v_mov_b32_e32 v47, v0
	v_mov_b32_e32 v48, v0
	v_mov_b32_e32 v49, v0
	v_mov_b32_e32 v50, v0
	v_mov_b32_e32 v51, v0
	v_mov_b32_e32 v52, v0
	v_mov_b32_e32 v53, v0
	v_mov_b32_e32 v54, v0
	v_mov_b32_e32 v55, v0
	v_mov_b32_e32 v56, v0
	v_mov_b32_e32 v57, v0
	v_mov_b32_e32 v58, v0
	v_mov_b32_e32 v59, v0
	v_mov_b32_e32 v60, v0
	v_mov_b32_e32 v61, v0
	v_mov_b32_e32 v62, v0
	v_mov_b32_e32 v63, v0
	v_mov_b32_e32 v64, v0
	v_mov_b32_e32 v65, v0
	v_mov_b32_e32 v66, v0
	v_mov_b32_e32 v67, v0
	v_mov_b32_e32 v68, v0
	v_mov_b32_e32 v69, v0
	v_mov_b32_e32 v70, v0
	v_mov_b32_e32 v71, v0
	v_mov_b32_e32 v72, v0
	v_mov_b32_e32 v73, v0
	v_mov_b32_e32 v74, v0
	v_mov_b32_e32 v75, v0
	v_mov_b32_e32 v76, v0
	v_mov_b32_e32 v77, v0
	v_mov_b32_e32 v78, v0
	v_mov_b32_e32 v79, v0
	v_mov_b32_e32 v112, v0
	v_mov_b32_e32 v113, v0
	v_mov_b32_e32 v114, v0
	v_mov_b32_e32 v115, v0
	v_mov_b32_e32 v116, v0
	v_mov_b32_e32 v117, v0
	v_mov_b32_e32 v118, v0
	v_mov_b32_e32 v119, v0
	v_mov_b32_e32 v120, v0
	v_mov_b32_e32 v121, v0
	v_mov_b32_e32 v122, v0
	v_mov_b32_e32 v123, v0
	v_mov_b32_e32 v124, v0
	v_mov_b32_e32 v125, v0
	v_mov_b32_e32 v126, v0
	v_mov_b32_e32 v127, v0
	v_mov_b32_e32 v80, v0
	v_mov_b32_e32 v81, v0
	v_mov_b32_e32 v82, v0
	v_mov_b32_e32 v83, v0
	v_mov_b32_e32 v84, v0
	v_mov_b32_e32 v85, v0
	v_mov_b32_e32 v86, v0
	v_mov_b32_e32 v87, v0
	v_mov_b32_e32 v88, v0
	v_mov_b32_e32 v89, v0
	v_mov_b32_e32 v90, v0
	v_mov_b32_e32 v91, v0
	v_mov_b32_e32 v92, v0
	v_mov_b32_e32 v93, v0
	v_mov_b32_e32 v94, v0
	v_mov_b32_e32 v95, v0
	v_mov_b32_e32 v96, v0
	v_mov_b32_e32 v97, v0
	v_mov_b32_e32 v98, v0
	v_mov_b32_e32 v99, v0
	v_mov_b32_e32 v100, v0
	v_mov_b32_e32 v101, v0
	v_mov_b32_e32 v102, v0
	v_mov_b32_e32 v103, v0
	v_mov_b32_e32 v104, v0
	v_mov_b32_e32 v105, v0
	v_mov_b32_e32 v106, v0
	v_mov_b32_e32 v107, v0
	v_mov_b32_e32 v108, v0
	v_mov_b32_e32 v109, v0
	v_mov_b32_e32 v110, v0
	v_mov_b32_e32 v111, v0
	s_mov_b64 s[54:55], 0x80
	v_lshrrev_b32_e32 v148, 6, v180
	v_lshlrev_b32_e32 v158, 11, v148
	v_mov_b32_e32 v149, 0x12000
	ds_read_b64 v[150:151], v149
	v_and_b32_e32 v144, 63, v180
	v_readfirstlane_b32 s53, v158
	v_lshrrev_b32_e32 v145, 5, v144
	v_bfe_u32 v146, v144, 1, 3
	v_xor_b32_e32 v146, v145, v146
	v_and_b32_e32 v147, 31, v144
	v_lshlrev_b32_e32 v147, 7, v147
	v_lshrrev_b32_e32 v147, 3, v144
	v_lshlrev_b32_e32 v158, 4, v147
	v_add_u32_e32 v159, 0x80, v158
	v_and_b32_e32 v147, 7, v144
	v_lshrrev_b32_e32 v145, 4, v144
	v_xor_b32_e32 v145, v147, v145
	v_lshrrev_b32_e32 v147, 5, v144
	v_sub_u32_e32 v182, v145, v147
	v_xor_b32_e32 v145, 4, v145
	v_add_u32_e32 v147, 2, v147
	v_sub_u32_e32 v184, v145, v147
	v_lshlrev_b32_e32 v182, 4, v182
	v_ashrrev_i32_e32 v183, 31, v182
	v_lshlrev_b32_e32 v184, 4, v184
	v_ashrrev_i32_e32 v185, 31, v184
	ds_bpermute_b32 v244, v158, v152
	ds_bpermute_b32 v245, v158, v153
	ds_bpermute_b32 v246, v159, v152
	ds_bpermute_b32 v247, v159, v153
	ds_bpermute_b32 v248, v158, v154
	ds_bpermute_b32 v249, v158, v155
	ds_bpermute_b32 v250, v159, v154
	ds_bpermute_b32 v251, v159, v155
	s_waitcnt lgkmcnt(0)
	ds_bpermute_b32 v186, v158, v136
	ds_bpermute_b32 v187, v158, v137
	ds_bpermute_b32 v234, v159, v136
	ds_bpermute_b32 v235, v159, v137
	ds_bpermute_b32 v236, v158, v138
	ds_bpermute_b32 v237, v158, v139
	ds_bpermute_b32 v238, v159, v138
	ds_bpermute_b32 v239, v159, v139
	ds_bpermute_b32 v240, v158, v140
	ds_bpermute_b32 v241, v158, v141
	ds_bpermute_b32 v242, v159, v140
	ds_bpermute_b32 v243, v159, v141
	ds_bpermute_b32 v152, v158, v142
	ds_bpermute_b32 v153, v158, v143
	ds_bpermute_b32 v154, v159, v142
	ds_bpermute_b32 v155, v159, v143
	s_waitcnt lgkmcnt(0)
	v_readfirstlane_b32 s56, v150
	v_readfirstlane_b32 s57, v151
	v_and_b32_e32 v147, 31, v144
	v_lshlrev_b32_e32 v147, 7, v147
	v_lshrrev_b32_e32 v145, 1, v148
	v_lshl_add_u32 v136, v145, 14, v147
	v_and_b32_e32 v145, 1, v148
	v_lshl_add_u32 v140, v145, 13, v147
	v_add_u32_e32 v140, 0x10000, v140
	v_xor_b32_e32 v147, 6, v146
	v_lshl_add_u32 v139, v147, 4, v136
	v_lshl_add_u32 v143, v147, 4, v140
	v_xor_b32_e32 v147, 4, v146
	v_lshl_add_u32 v138, v147, 4, v136
	v_lshl_add_u32 v142, v147, 4, v140
	v_xor_b32_e32 v147, 2, v146
	v_lshl_add_u32 v137, v147, 4, v136
	v_lshl_add_u32 v141, v147, 4, v140
	v_xor_b32_e32 v147, 0, v146
	v_lshl_add_u32 v136, v147, 4, v136
	v_lshl_add_u32 v140, v147, 4, v140
	v_lshl_add_u64 v[186:187], v[186:187], 0, v[182:183]
	v_lshl_add_u64 v[234:235], v[234:235], 0, v[184:185]
	v_lshl_add_u64 v[236:237], v[236:237], 0, v[182:183]
	v_lshl_add_u64 v[238:239], v[238:239], 0, v[184:185]
	v_lshl_add_u64 v[240:241], v[240:241], 0, v[182:183]
	v_lshl_add_u64 v[242:243], v[242:243], 0, v[184:185]
	v_lshl_add_u64 v[152:153], v[152:153], 0, v[182:183]
	v_lshl_add_u64 v[154:155], v[154:155], 0, v[184:185]
	v_lshl_add_u64 v[244:245], v[244:245], 0, v[182:183]
	v_lshl_add_u64 v[246:247], v[246:247], 0, v[184:185]
	v_lshl_add_u64 v[248:249], v[248:249], 0, v[182:183]
	v_lshl_add_u64 v[250:251], v[250:251], 0, v[184:185]
	s_mov_b32 s58, s53
	s_add_i32 m0, s58, 0x0
	s_nop 0
	global_load_lds_dwordx4 v[186:187], off
	s_add_i32 m0, s58, 0x400
	v_lshl_add_u64 v[186:187], v[186:187], 0, s[54:55]
	global_load_lds_dwordx4 v[234:235], off
	s_add_i32 m0, s58, 0x2000
	v_lshl_add_u64 v[234:235], v[234:235], 0, s[54:55]
	global_load_lds_dwordx4 v[236:237], off
	s_add_i32 m0, s58, 0x2400
	v_lshl_add_u64 v[236:237], v[236:237], 0, s[54:55]
	global_load_lds_dwordx4 v[238:239], off
	s_add_i32 m0, s58, 0x4000
	v_lshl_add_u64 v[238:239], v[238:239], 0, s[54:55]
	global_load_lds_dwordx4 v[240:241], off
	s_add_i32 m0, s58, 0x4400
	v_lshl_add_u64 v[240:241], v[240:241], 0, s[54:55]
	global_load_lds_dwordx4 v[242:243], off
	s_add_i32 m0, s58, 0x6000
	v_lshl_add_u64 v[242:243], v[242:243], 0, s[54:55]
	global_load_lds_dwordx4 v[152:153], off
	s_add_i32 m0, s58, 0x6400
	v_lshl_add_u64 v[152:153], v[152:153], 0, s[54:55]
	global_load_lds_dwordx4 v[154:155], off
	v_lshl_add_u64 v[154:155], v[154:155], 0, s[54:55]
	s_add_i32 s58, s53, 0x10000
	s_add_i32 m0, s58, 0x0
	s_nop 0
	global_load_lds_dwordx4 v[244:245], off
	s_add_i32 m0, s58, 0x400
	v_lshl_add_u64 v[244:245], v[244:245], 0, s[54:55]
	global_load_lds_dwordx4 v[246:247], off
	s_add_i32 m0, s58, 0x2000
	v_lshl_add_u64 v[246:247], v[246:247], 0, s[54:55]
	global_load_lds_dwordx4 v[248:249], off
	s_add_i32 m0, s58, 0x2400
	v_lshl_add_u64 v[248:249], v[248:249], 0, s[54:55]
	global_load_lds_dwordx4 v[250:251], off
	v_lshl_add_u64 v[250:251], v[250:251], 0, s[54:55]
	s_mov_b32 s24, 0
	s_mov_b32 s25, 0
.Lg_ph11b_top:
	s_waitcnt vmcnt(0)
	s_waitcnt lgkmcnt(0)
	s_barrier
	s_cmp_eq_u32 s24, 15
	s_cbranch_scc1 .Lg_ph11b_noA
	s_xor_b32 s58, s25, 0x8000
	s_add_i32 s58, s58, s53
	s_add_i32 m0, s58, 0x0
	s_nop 0
	global_load_lds_dwordx4 v[186:187], off
	s_add_i32 m0, s58, 0x400
	v_lshl_add_u64 v[186:187], v[186:187], 0, s[54:55]
	global_load_lds_dwordx4 v[234:235], off
	s_add_i32 m0, s58, 0x2000
	v_lshl_add_u64 v[234:235], v[234:235], 0, s[54:55]
	global_load_lds_dwordx4 v[236:237], off
	s_add_i32 m0, s58, 0x2400
	v_lshl_add_u64 v[236:237], v[236:237], 0, s[54:55]
	global_load_lds_dwordx4 v[238:239], off
	s_add_i32 m0, s58, 0x4000
	v_lshl_add_u64 v[238:239], v[238:239], 0, s[54:55]
	global_load_lds_dwordx4 v[240:241], off
	s_add_i32 m0, s58, 0x4400
	v_lshl_add_u64 v[240:241], v[240:241], 0, s[54:55]
	global_load_lds_dwordx4 v[242:243], off
	s_add_i32 m0, s58, 0x6000
	v_lshl_add_u64 v[242:243], v[242:243], 0, s[54:55]
	global_load_lds_dwordx4 v[152:153], off
	s_add_i32 m0, s58, 0x6400
	v_lshl_add_u64 v[152:153], v[152:153], 0, s[54:55]
	global_load_lds_dwordx4 v[154:155], off
	v_lshl_add_u64 v[154:155], v[154:155], 0, s[54:55]
.Lg_ph11b_noA:
	ds_read_b128 v[190:193], v140
	ds_read_b128 v[194:197], v140 offset:4096
	ds_read_b128 v[198:201], v141
	ds_read_b128 v[202:205], v141 offset:4096
	ds_read_b128 v[206:209], v142
	ds_read_b128 v[222:225], v142 offset:4096
	ds_read_b128 v[226:229], v143
	ds_read_b128 v[230:233], v143 offset:4096
	ds_read_b128 v[144:147], v136
	ds_read_b128 v[148:151], v136 offset:4096
	ds_read_b128 v[156:159], v136 offset:8192
	ds_read_b128 v[182:185], v136 offset:12288
	s_waitcnt lgkmcnt(4)
	s_barrier
	s_cmp_eq_u32 s24, 15
	s_cbranch_scc1 .Lg_ph11b_noB
	s_add_i32 s58, s53, 0x10000
	s_add_i32 m0, s58, 0x0
	s_nop 0
	global_load_lds_dwordx4 v[244:245], off
	s_add_i32 m0, s58, 0x400
	v_lshl_add_u64 v[244:245], v[244:245], 0, s[54:55]
	global_load_lds_dwordx4 v[246:247], off
	s_add_i32 m0, s58, 0x2000
	v_lshl_add_u64 v[246:247], v[246:247], 0, s[54:55]
	global_load_lds_dwordx4 v[248:249], off
	s_add_i32 m0, s58, 0x2400
	v_lshl_add_u64 v[248:249], v[248:249], 0, s[54:55]
	global_load_lds_dwordx4 v[250:251], off
	v_lshl_add_u64 v[250:251], v[250:251], 0, s[54:55]
.Lg_ph11b_noB:
	s_waitcnt lgkmcnt(3)
	v_mfma_f32_32x32x16_bf16 v[0:15], v[144:147], v[190:193], v[0:15]
	v_mfma_f32_32x32x16_bf16 v[16:31], v[144:147], v[194:197], v[16:31]
	ds_read_b128 v[144:147], v137
	s_waitcnt lgkmcnt(3)
	v_mfma_f32_32x32x16_bf16 v[32:47], v[148:151], v[190:193], v[32:47]
	v_mfma_f32_32x32x16_bf16 v[48:63], v[148:151], v[194:197], v[48:63]
	ds_read_b128 v[148:151], v137 offset:4096
	s_waitcnt lgkmcnt(3)
	v_mfma_f32_32x32x16_bf16 v[64:79], v[156:159], v[190:193], v[64:79]
	v_mfma_f32_32x32x16_bf16 v[112:127], v[156:159], v[194:197], v[112:127]
	ds_read_b128 v[156:159], v137 offset:8192
	s_waitcnt lgkmcnt(3)
	v_mfma_f32_32x32x16_bf16 v[80:95], v[182:185], v[190:193], v[80:95]
	v_mfma_f32_32x32x16_bf16 v[96:111], v[182:185], v[194:197], v[96:111]
	ds_read_b128 v[182:185], v137 offset:12288
	s_waitcnt lgkmcnt(3)
	v_mfma_f32_32x32x16_bf16 v[0:15], v[144:147], v[198:201], v[0:15]
	v_mfma_f32_32x32x16_bf16 v[16:31], v[144:147], v[202:205], v[16:31]
	ds_read_b128 v[144:147], v138
	s_waitcnt lgkmcnt(3)
	v_mfma_f32_32x32x16_bf16 v[32:47], v[148:151], v[198:201], v[32:47]
	v_mfma_f32_32x32x16_bf16 v[48:63], v[148:151], v[202:205], v[48:63]
	ds_read_b128 v[148:151], v138 offset:4096
	s_waitcnt lgkmcnt(3)
	v_mfma_f32_32x32x16_bf16 v[64:79], v[156:159], v[198:201], v[64:79]
	v_mfma_f32_32x32x16_bf16 v[112:127], v[156:159], v[202:205], v[112:127]
	ds_read_b128 v[156:159], v138 offset:8192
	s_waitcnt lgkmcnt(3)
	v_mfma_f32_32x32x16_bf16 v[80:95], v[182:185], v[198:201], v[80:95]
	v_mfma_f32_32x32x16_bf16 v[96:111], v[182:185], v[202:205], v[96:111]
	ds_read_b128 v[182:185], v138 offset:12288
	s_waitcnt lgkmcnt(3)
	v_mfma_f32_32x32x16_bf16 v[0:15], v[144:147], v[206:209], v[0:15]
	v_mfma_f32_32x32x16_bf16 v[16:31], v[144:147], v[222:225], v[16:31]
	ds_read_b128 v[144:147], v139
	s_waitcnt lgkmcnt(3)
	v_mfma_f32_32x32x16_bf16 v[32:47], v[148:151], v[206:209], v[32:47]
	v_mfma_f32_32x32x16_bf16 v[48:63], v[148:151], v[222:225], v[48:63]
	ds_read_b128 v[148:151], v139 offset:4096
	s_waitcnt lgkmcnt(3)
	v_mfma_f32_32x32x16_bf16 v[64:79], v[156:159], v[206:209], v[64:79]
	v_mfma_f32_32x32x16_bf16 v[112:127], v[156:159], v[222:225], v[112:127]
	ds_read_b128 v[156:159], v139 offset:8192
	s_waitcnt lgkmcnt(3)
	v_mfma_f32_32x32x16_bf16 v[80:95], v[182:185], v[206:209], v[80:95]
	v_mfma_f32_32x32x16_bf16 v[96:111], v[182:185], v[222:225], v[96:111]
	ds_read_b128 v[182:185], v139 offset:12288
	s_waitcnt lgkmcnt(3)
	v_mfma_f32_32x32x16_bf16 v[0:15], v[144:147], v[226:229], v[0:15]
	v_mfma_f32_32x32x16_bf16 v[16:31], v[144:147], v[230:233], v[16:31]
	s_waitcnt lgkmcnt(2)
	v_mfma_f32_32x32x16_bf16 v[32:47], v[148:151], v[226:229], v[32:47]
	v_mfma_f32_32x32x16_bf16 v[48:63], v[148:151], v[230:233], v[48:63]
	s_waitcnt lgkmcnt(1)
	v_mfma_f32_32x32x16_bf16 v[64:79], v[156:159], v[226:229], v[64:79]
	v_mfma_f32_32x32x16_bf16 v[112:127], v[156:159], v[230:233], v[112:127]
	s_waitcnt lgkmcnt(0)
	v_mfma_f32_32x32x16_bf16 v[80:95], v[182:185], v[226:229], v[80:95]
	v_mfma_f32_32x32x16_bf16 v[96:111], v[182:185], v[230:233], v[96:111]
	v_xor_b32_e32 v136, 0x8000, v136
	v_xor_b32_e32 v137, 0x8000, v137
	v_xor_b32_e32 v138, 0x8000, v138
	v_xor_b32_e32 v139, 0x8000, v139
	s_xor_b32 s25, s25, 0x8000
	s_add_i32 s24, s24, 1
	s_cmp_eq_u32 s24, 16
	s_cbranch_scc0 .Lg_ph11b_top
	v_mov_b32_e32 v149, 0x12000
	v_mov_b32_e32 v150, s56
	v_mov_b32_e32 v151, s57
	ds_write_b64 v149, v[150:151]
	s_waitcnt vmcnt(0)
	v_mov_b32_e32 v130, v180
	v_add_u32_e32 v192, 0x400, v166
	v_add_u32_e32 v191, 0x1000, v166
	v_add_u32_e32 v190, 0x1400, v166
	v_add_u32_e32 v189, 0x2000, v166
	v_add_u32_e32 v182, 0x2400, v166
	v_add_u32_e32 v183, 0x3000, v166
	v_add_u32_e32 v184, 0x3200, v166
	v_add_u32_e32 v185, 0x3400, v166
	v_add_u32_e32 v186, 0x3600, v166
	v_add_u32_e32 v187, 0x4000, v166
	v_add_u32_e32 v159, 0x4400, v166
	v_add_u32_e32 v179, 0x4800, v166
	v_add_u32_e32 v181, 0x5000, v166
	v_add_u32_e32 v156, 0x5400, v166
	v_add_u32_e32 v157, 0x5800, v166
	v_add_u32_e32 v158, 0x6000, v166
	v_add_u32_e32 v150, 0x6400, v166
	v_add_u32_e32 v151, 0x6800, v166
	v_add_u32_e32 v152, 0x7200, v166
	v_add_u32_e32 v153, 0x7400, v166
	v_add_u32_e32 v154, 0x7600, v166
	v_add_u32_e32 v155, 0x7800, v166
	v_add_u32_e32 v149, 0x8400, v166
	v_add_u32_e32 v148, 0x8800, v166
	v_add_u32_e32 v147, 0x9400, v166
	v_add_u32_e32 v146, 0x9800, v166
	v_add_u32_e32 v145, 0xa400, v166
	v_add_u32_e32 v140, 0xa800, v166
	v_add_u32_e32 v141, 0xb400, v166
	v_add_u32_e32 v142, 0xb600, v166
	v_add_u32_e32 v143, 0xb800, v166
	v_add_u32_e32 v144, 0xba00, v166
	s_waitcnt vmcnt(0)
	s_barrier
	s_and_saveexec_b64 s[24:25], s[6:7]
	s_cbranch_execz .LBB0_1187
	v_add_u32_e32 v133, 0xc400, v166
	ds_write2_b32 v166, v0, v16 offset1:32
	ds_write2_b32 v166, v1, v17 offset0:132 offset1:164
	ds_write2_b32 v192, v2, v18 offset0:8 offset1:40
	ds_write2_b32 v192, v3, v19 offset0:140 offset1:172
	ds_write2_b32 v191, v4, v20 offset0:32 offset1:64
	ds_write2_b32 v191, v5, v21 offset0:164 offset1:196
	ds_write2_b32 v190, v6, v22 offset0:40 offset1:72
	ds_write2_b32 v190, v7, v23 offset0:172 offset1:204
	ds_write2_b32 v189, v8, v24 offset0:64 offset1:96
	ds_write2_b32 v189, v9, v25 offset0:196 offset1:228
	ds_write2_b32 v182, v10, v26 offset0:72 offset1:104
	ds_write2_b32 v182, v11, v27 offset0:204 offset1:236
	ds_write2_b32 v183, v12, v28 offset0:96 offset1:128
	ds_write2_b32 v184, v13, v29 offset0:100 offset1:132
	ds_write2_b32 v185, v14, v30 offset0:104 offset1:136
	ds_write2_b32 v186, v15, v31 offset0:108 offset1:140
	ds_write2_b32 v187, v32, v48 offset0:128 offset1:160
	ds_write2_b32 v159, v33, v49 offset0:4 offset1:36
	ds_write2_b32 v159, v34, v50 offset0:136 offset1:168
	ds_write2_b32 v179, v35, v51 offset0:12 offset1:44
	ds_write2_b32 v181, v36, v52 offset0:160 offset1:192
	ds_write2_b32 v156, v37, v53 offset0:36 offset1:68
	ds_write2_b32 v156, v38, v54 offset0:168 offset1:200
	ds_write2_b32 v157, v39, v55 offset0:44 offset1:76
	ds_write2_b32 v158, v40, v56 offset0:192 offset1:224
	ds_write2_b32 v150, v41, v57 offset0:68 offset1:100
	ds_write2_b32 v150, v42, v58 offset0:200 offset1:232
	ds_write2_b32 v151, v43, v59 offset0:76 offset1:108
	ds_write2_b32 v152, v44, v60 offset0:96 offset1:128
	ds_write2_b32 v153, v45, v61 offset0:100 offset1:132
	ds_write2_b32 v154, v46, v62 offset0:104 offset1:136
	ds_write2_b32 v155, v47, v63 offset0:108 offset1:140
	ds_write2_b32 v149, v64, v112 offset1:32
	ds_write2_b32 v149, v65, v113 offset0:132 offset1:164
	ds_write2_b32 v148, v66, v114 offset0:8 offset1:40
	ds_write2_b32 v148, v67, v115 offset0:140 offset1:172
	ds_write2_b32 v147, v68, v116 offset0:32 offset1:64
	ds_write2_b32 v147, v69, v117 offset0:164 offset1:196
	ds_write2_b32 v146, v70, v118 offset0:40 offset1:72
	ds_write2_b32 v146, v71, v119 offset0:172 offset1:204
	ds_write2_b32 v145, v72, v120 offset0:64 offset1:96
	ds_write2_b32 v145, v73, v121 offset0:196 offset1:228
	ds_write2_b32 v140, v74, v122 offset0:72 offset1:104
	ds_write2_b32 v140, v75, v123 offset0:204 offset1:236
	ds_write2_b32 v141, v76, v124 offset0:96 offset1:128
	ds_write2_b32 v142, v77, v125 offset0:100 offset1:132
	ds_write2_b32 v143, v78, v126 offset0:104 offset1:136
	ds_write2_b32 v144, v79, v127 offset0:108 offset1:140
	ds_write2_b32 v133, v80, v96 offset0:128 offset1:160
	v_add_u32_e32 v133, 0xc800, v166
	ds_write2_b32 v133, v81, v97 offset0:4 offset1:36
	ds_write2_b32 v133, v82, v98 offset0:136 offset1:168
	v_add_u32_e32 v133, 0xcc00, v166
	ds_write2_b32 v133, v83, v99 offset0:12 offset1:44
	v_add_u32_e32 v133, 0xd400, v166
	ds_write2_b32 v133, v84, v100 offset0:160 offset1:192
	v_add_u32_e32 v133, 0xd800, v166
	ds_write2_b32 v133, v85, v101 offset0:36 offset1:68
	ds_write2_b32 v133, v86, v102 offset0:168 offset1:200
	v_add_u32_e32 v133, 0xdc00, v166
	ds_write2_b32 v133, v87, v103 offset0:44 offset1:76
	v_add_u32_e32 v133, 0xe400, v166
	ds_write2_b32 v133, v88, v104 offset0:192 offset1:224
	v_add_u32_e32 v133, 0xe800, v166
	ds_write2_b32 v133, v89, v105 offset0:68 offset1:100
	ds_write2_b32 v133, v90, v106 offset0:200 offset1:232
	v_add_u32_e32 v133, 0xec00, v166
	ds_write2_b32 v133, v91, v107 offset0:76 offset1:108
	v_add_u32_e32 v133, 0xf600, v166
	ds_write2_b32 v133, v92, v108 offset0:96 offset1:128
	v_add_u32_e32 v133, 0xf800, v166
	ds_write2_b32 v133, v93, v109 offset0:100 offset1:132
	v_add_u32_e32 v133, 0xfa00, v166
	ds_write2_b32 v133, v94, v110 offset0:104 offset1:136
	v_add_u32_e32 v133, 0xfc00, v166
	ds_write2_b32 v133, v95, v111 offset0:108 offset1:140

.LBB0_1315:
	s_lshr_b32 s4, s23, 3
	s_or_b32 s4, s4, s24
	s_lshl_b32 s30, s4, 18
	s_and_b32 s29, s23, 7
	v_or_b32_e32 v1, s30, v129
	s_lshl_b32 s4, s29, 18
	s_add_u32 s16, s18, s4
	v_or_b32_e32 v0, v1, v128
	v_readfirstlane_b32 s4, v148
	v_lshlrev_b32_e32 v130, 1, v0
	s_mov_b32 m0, s4
	v_readfirstlane_b32 s4, v157
	v_add_lshl_u32 v0, v1, v154, 1
	s_waitcnt vmcnt(0)
	s_barrier
	s_nop 0
	s_mov_b32 m0, s4
	v_readfirstlane_b32 s4, v158
	s_addc_u32 s17, s19, 0
	v_add_lshl_u32 v2, v1, v155, 1
	s_nop 0
	s_mov_b32 m0, s4
	v_readfirstlane_b32 s4, v159
	v_add_lshl_u32 v4, v1, v156, 1
	v_lshl_add_u64 v[6:7], s[16:17], 0, v[132:133]
	s_nop 0
	s_mov_b32 m0, s4
	v_readfirstlane_b32 s4, v160
	v_lshl_add_u64 v[136:137], v[6:7], 0, v[134:135]
	s_nop 0
	s_mov_b32 m0, s4
	v_readfirstlane_b32 s4, v161
	v_lshl_add_u64 v[138:139], s[2:3], 0, v[130:131]
	v_mov_b32_e32 v1, v131
	v_lshl_add_u64 v[146:147], v[136:137], 0, s[10:11]
	s_nop 0
	s_mov_b32 m0, s4
	v_readfirstlane_b32 s4, v162
	v_lshl_add_u64 v[140:141], s[2:3], 0, v[0:1]
	v_mov_b32_e32 v3, v131
	s_nop 0
	v_lshl_add_u64 v[0:1], v[138:139], 0, 64
	s_mov_b32 m0, s4
	v_readfirstlane_b32 s4, v163
	v_lshl_add_u64 v[142:143], s[2:3], 0, v[2:3]
	v_mov_b32_e32 v5, v131
	s_nop 0
	v_lshl_add_u64 v[0:1], v[140:141], 0, 64
	s_mov_b32 m0, s4
	v_readfirstlane_b32 s4, v164
	v_lshl_add_u64 v[144:145], s[2:3], 0, v[4:5]
	s_nop 0
	v_lshl_add_u64 v[0:1], v[142:143], 0, 64
	s_mov_b32 m0, s4
	v_readfirstlane_b32 s4, v165
	s_nop 0
	v_lshl_add_u64 v[0:1], v[144:145], 0, 64
	s_mov_b32 m0, s4
	v_readfirstlane_b32 s4, v166
	s_nop 0
	v_lshl_add_u64 v[0:1], v[136:137], 0, 64
	s_mov_b32 m0, s4
	v_readfirstlane_b32 s4, v167
	s_nop 0
	v_lshl_add_u64 v[0:1], v[136:137], 0, s[12:13]
	s_mov_b32 m0, s4
	s_mov_b32 s16, s5
	s_nop 0
	s_mov_b32 s17, 2
	s_mov_b32 s31, s5
	v_mov_b32_e32 v0, 0
	v_mov_b32_e32 v1, v131
	v_mov_b32_e32 v2, v131
	v_mov_b32_e32 v4, v131
	v_mov_b32_e32 v6, v131
	v_mov_b32_e32 v7, v131
	v_mov_b32_e32 v8, v131
	v_mov_b32_e32 v9, v131
	v_mov_b32_e32 v10, v131
	v_mov_b32_e32 v11, v131
	v_mov_b32_e32 v12, v131
	v_mov_b32_e32 v13, v131
	v_mov_b32_e32 v14, v131
	v_mov_b32_e32 v15, v131
	v_mov_b32_e32 v16, 0
	v_mov_b32_e32 v17, v131
	v_mov_b32_e32 v18, v131
	v_mov_b32_e32 v19, v131
	v_mov_b32_e32 v20, v131
	v_mov_b32_e32 v21, v131
	v_mov_b32_e32 v22, v131
	v_mov_b32_e32 v23, v131
	v_mov_b32_e32 v24, v131
	v_mov_b32_e32 v25, v131
	v_mov_b32_e32 v26, v131
	v_mov_b32_e32 v27, v131
	v_mov_b32_e32 v28, v131
	v_mov_b32_e32 v29, v131
	v_mov_b32_e32 v30, v131
	v_mov_b32_e32 v31, v131
	v_mov_b32_e32 v32, 0
	v_mov_b32_e32 v33, v131
	v_mov_b32_e32 v34, v131
	v_mov_b32_e32 v35, v131
	v_mov_b32_e32 v36, v131
	v_mov_b32_e32 v37, v131
	v_mov_b32_e32 v38, v131
	v_mov_b32_e32 v39, v131
	v_mov_b32_e32 v40, v131
	v_mov_b32_e32 v41, v131
	v_mov_b32_e32 v42, v131
	v_mov_b32_e32 v43, v131
	v_mov_b32_e32 v44, v131
	v_mov_b32_e32 v45, v131
	v_mov_b32_e32 v46, v131
	v_mov_b32_e32 v47, v131
	v_mov_b32_e32 v48, 0
	v_mov_b32_e32 v49, v131
	v_mov_b32_e32 v50, v131
	v_mov_b32_e32 v51, v131
	v_mov_b32_e32 v52, v131
	v_mov_b32_e32 v53, v131
	v_mov_b32_e32 v54, v131
	v_mov_b32_e32 v55, v131
	v_mov_b32_e32 v56, v131
	v_mov_b32_e32 v57, v131
	v_mov_b32_e32 v58, v131
	v_mov_b32_e32 v59, v131
	v_mov_b32_e32 v60, v131
	v_mov_b32_e32 v61, v131
	v_mov_b32_e32 v62, v131
	v_mov_b32_e32 v63, v131
	v_mov_b32_e32 v64, 0
	v_mov_b32_e32 v65, v131
	v_mov_b32_e32 v66, v131
	v_mov_b32_e32 v67, v131
	v_mov_b32_e32 v68, v131
	v_mov_b32_e32 v69, v131
	v_mov_b32_e32 v70, v131
	v_mov_b32_e32 v71, v131
	v_mov_b32_e32 v72, v131
	v_mov_b32_e32 v73, v131
	v_mov_b32_e32 v74, v131
	v_mov_b32_e32 v75, v131
	v_mov_b32_e32 v76, v131
	v_mov_b32_e32 v77, v131
	v_mov_b32_e32 v78, v131
	v_mov_b32_e32 v79, v131
	v_mov_b32_e32 v80, 0
	v_mov_b32_e32 v81, v131
	v_mov_b32_e32 v82, v131
	v_mov_b32_e32 v83, v131
	v_mov_b32_e32 v84, v131
	v_mov_b32_e32 v85, v131
	v_mov_b32_e32 v86, v131
	v_mov_b32_e32 v87, v131
	v_mov_b32_e32 v88, v131
	v_mov_b32_e32 v89, v131
	v_mov_b32_e32 v90, v131
	v_mov_b32_e32 v91, v131
	v_mov_b32_e32 v92, v131
	v_mov_b32_e32 v93, v131
	v_mov_b32_e32 v94, v131
	v_mov_b32_e32 v95, v131
	v_mov_b32_e32 v96, 0
	v_mov_b32_e32 v97, v131
	v_mov_b32_e32 v98, v131
	v_mov_b32_e32 v99, v131
	v_mov_b32_e32 v100, v131
	v_mov_b32_e32 v101, v131
	v_mov_b32_e32 v102, v131
	v_mov_b32_e32 v103, v131
	v_mov_b32_e32 v104, v131
	v_mov_b32_e32 v105, v131
	v_mov_b32_e32 v106, v131
	v_mov_b32_e32 v107, v131
	v_mov_b32_e32 v108, v131
	v_mov_b32_e32 v109, v131
	v_mov_b32_e32 v110, v131
	v_mov_b32_e32 v111, v131
	v_mov_b32_e32 v112, 0
	v_mov_b32_e32 v113, v131
	v_mov_b32_e32 v114, v131
	v_mov_b32_e32 v115, v131
	v_mov_b32_e32 v116, v131
	v_mov_b32_e32 v117, v131
	v_mov_b32_e32 v118, v131
	v_mov_b32_e32 v119, v131
	v_mov_b32_e32 v120, v131
	v_mov_b32_e32 v121, v131
	v_mov_b32_e32 v122, v131
	v_mov_b32_e32 v123, v131
	v_mov_b32_e32 v124, v131
	v_mov_b32_e32 v125, v131
	v_mov_b32_e32 v126, v131
	v_mov_b32_e32 v127, v131
	s_mov_b64 s[54:55], 0x80
	v_lshrrev_b32_e32 v174, 6, v180
	v_lshlrev_b32_e32 v184, 11, v174
	v_mov_b32_e32 v175, 0x12000
	ds_read_b64 v[176:177], v175
	v_and_b32_e32 v170, 63, v180
	v_readfirstlane_b32 s53, v184
	v_lshrrev_b32_e32 v171, 5, v170
	v_bfe_u32 v172, v170, 1, 3
	v_xor_b32_e32 v172, v171, v172
	v_and_b32_e32 v173, 31, v170
	v_lshlrev_b32_e32 v173, 7, v173
	v_lshrrev_b32_e32 v173, 3, v170
	v_lshlrev_b32_e32 v184, 4, v173
	v_add_u32_e32 v185, 0x80, v184
	v_and_b32_e32 v173, 7, v170
	v_lshrrev_b32_e32 v171, 4, v170
	v_xor_b32_e32 v171, v173, v171
	v_lshrrev_b32_e32 v173, 5, v170
	v_sub_u32_e32 v190, v171, v173
	v_xor_b32_e32 v171, 4, v171
	v_add_u32_e32 v173, 2, v173
	v_sub_u32_e32 v192, v171, v173
	v_lshlrev_b32_e32 v190, 4, v190
	v_ashrrev_i32_e32 v191, 31, v190
	v_lshlrev_b32_e32 v192, 4, v192
	v_ashrrev_i32_e32 v193, 31, v192
	ds_bpermute_b32 v242, v184, v136
	ds_bpermute_b32 v243, v184, v137
	ds_bpermute_b32 v244, v185, v136
	ds_bpermute_b32 v245, v185, v137
	ds_bpermute_b32 v246, v184, v146
	ds_bpermute_b32 v247, v184, v147
	ds_bpermute_b32 v248, v185, v146
	ds_bpermute_b32 v249, v185, v147
	s_waitcnt lgkmcnt(0)
	ds_bpermute_b32 v178, v184, v138
	ds_bpermute_b32 v179, v184, v139
	ds_bpermute_b32 v186, v185, v138
	ds_bpermute_b32 v187, v185, v139
	ds_bpermute_b32 v234, v184, v140
	ds_bpermute_b32 v235, v184, v141
	ds_bpermute_b32 v236, v185, v140
	ds_bpermute_b32 v237, v185, v141
	ds_bpermute_b32 v238, v184, v142
	ds_bpermute_b32 v239, v184, v143
	ds_bpermute_b32 v240, v185, v142
	ds_bpermute_b32 v241, v185, v143
	ds_bpermute_b32 v136, v184, v144
	ds_bpermute_b32 v137, v184, v145
	ds_bpermute_b32 v146, v185, v144
	ds_bpermute_b32 v147, v185, v145
	s_waitcnt lgkmcnt(0)
	v_readfirstlane_b32 s56, v176
	v_readfirstlane_b32 s57, v177
	v_and_b32_e32 v173, 31, v170
	v_lshlrev_b32_e32 v173, 7, v173
	v_lshrrev_b32_e32 v171, 1, v174
	v_lshl_add_u32 v138, v171, 14, v173
	v_and_b32_e32 v171, 1, v174
	v_lshl_add_u32 v142, v171, 13, v173
	v_add_u32_e32 v142, 0x10000, v142
	v_xor_b32_e32 v173, 6, v172
	v_lshl_add_u32 v141, v173, 4, v138
	v_lshl_add_u32 v145, v173, 4, v142
	v_xor_b32_e32 v173, 4, v172
	v_lshl_add_u32 v140, v173, 4, v138
	v_lshl_add_u32 v144, v173, 4, v142
	v_xor_b32_e32 v173, 2, v172
	v_lshl_add_u32 v139, v173, 4, v138
	v_lshl_add_u32 v143, v173, 4, v142
	v_xor_b32_e32 v173, 0, v172
	v_lshl_add_u32 v138, v173, 4, v138
	v_lshl_add_u32 v142, v173, 4, v142
	v_lshl_add_u64 v[178:179], v[178:179], 0, v[190:191]
	v_lshl_add_u64 v[186:187], v[186:187], 0, v[192:193]
	v_lshl_add_u64 v[234:235], v[234:235], 0, v[190:191]
	v_lshl_add_u64 v[236:237], v[236:237], 0, v[192:193]
	v_lshl_add_u64 v[238:239], v[238:239], 0, v[190:191]
	v_lshl_add_u64 v[240:241], v[240:241], 0, v[192:193]
	v_lshl_add_u64 v[136:137], v[136:137], 0, v[190:191]
	v_lshl_add_u64 v[146:147], v[146:147], 0, v[192:193]
	v_lshl_add_u64 v[242:243], v[242:243], 0, v[190:191]
	v_lshl_add_u64 v[244:245], v[244:245], 0, v[192:193]
	v_lshl_add_u64 v[246:247], v[246:247], 0, v[190:191]
	v_lshl_add_u64 v[248:249], v[248:249], 0, v[192:193]
	s_mov_b32 s58, s53
	s_add_i32 m0, s58, 0x0
	s_nop 0
	global_load_lds_dwordx4 v[178:179], off
	s_add_i32 m0, s58, 0x400
	v_lshl_add_u64 v[178:179], v[178:179], 0, s[54:55]
	global_load_lds_dwordx4 v[186:187], off
	s_add_i32 m0, s58, 0x2000
	v_lshl_add_u64 v[186:187], v[186:187], 0, s[54:55]
	global_load_lds_dwordx4 v[234:235], off
	s_add_i32 m0, s58, 0x2400
	v_lshl_add_u64 v[234:235], v[234:235], 0, s[54:55]
	global_load_lds_dwordx4 v[236:237], off
	s_add_i32 m0, s58, 0x4000
	v_lshl_add_u64 v[236:237], v[236:237], 0, s[54:55]
	global_load_lds_dwordx4 v[238:239], off
	s_add_i32 m0, s58, 0x4400
	v_lshl_add_u64 v[238:239], v[238:239], 0, s[54:55]
	global_load_lds_dwordx4 v[240:241], off
	s_add_i32 m0, s58, 0x6000
	v_lshl_add_u64 v[240:241], v[240:241], 0, s[54:55]
	global_load_lds_dwordx4 v[136:137], off
	s_add_i32 m0, s58, 0x6400
	v_lshl_add_u64 v[136:137], v[136:137], 0, s[54:55]
	global_load_lds_dwordx4 v[146:147], off
	v_lshl_add_u64 v[146:147], v[146:147], 0, s[54:55]
	s_add_i32 s58, s53, 0x10000
	s_add_i32 m0, s58, 0x0
	s_nop 0
	global_load_lds_dwordx4 v[242:243], off
	s_add_i32 m0, s58, 0x400
	v_lshl_add_u64 v[242:243], v[242:243], 0, s[54:55]
	global_load_lds_dwordx4 v[244:245], off
	s_add_i32 m0, s58, 0x2000
	v_lshl_add_u64 v[244:245], v[244:245], 0, s[54:55]
	global_load_lds_dwordx4 v[246:247], off
	s_add_i32 m0, s58, 0x2400
	v_lshl_add_u64 v[246:247], v[246:247], 0, s[54:55]
	global_load_lds_dwordx4 v[248:249], off
	v_lshl_add_u64 v[248:249], v[248:249], 0, s[54:55]
	s_mov_b32 s16, 0
	s_mov_b32 s17, 0
.Lg_ph13_top:
	s_waitcnt vmcnt(0)
	s_waitcnt lgkmcnt(0)
	s_barrier
	s_cmp_eq_u32 s16, 15
	s_cbranch_scc1 .Lg_ph13_noA
	s_xor_b32 s58, s17, 0x8000
	s_add_i32 s58, s58, s53
	s_add_i32 m0, s58, 0x0
	s_nop 0
	global_load_lds_dwordx4 v[178:179], off
	s_add_i32 m0, s58, 0x400
	v_lshl_add_u64 v[178:179], v[178:179], 0, s[54:55]
	global_load_lds_dwordx4 v[186:187], off
	s_add_i32 m0, s58, 0x2000
	v_lshl_add_u64 v[186:187], v[186:187], 0, s[54:55]
	global_load_lds_dwordx4 v[234:235], off
	s_add_i32 m0, s58, 0x2400
	v_lshl_add_u64 v[234:235], v[234:235], 0, s[54:55]
	global_load_lds_dwordx4 v[236:237], off
	s_add_i32 m0, s58, 0x4000
	v_lshl_add_u64 v[236:237], v[236:237], 0, s[54:55]
	global_load_lds_dwordx4 v[238:239], off
	s_add_i32 m0, s58, 0x4400
	v_lshl_add_u64 v[238:239], v[238:239], 0, s[54:55]
	global_load_lds_dwordx4 v[240:241], off
	s_add_i32 m0, s58, 0x6000
	v_lshl_add_u64 v[240:241], v[240:241], 0, s[54:55]
	global_load_lds_dwordx4 v[136:137], off
	s_add_i32 m0, s58, 0x6400
	v_lshl_add_u64 v[136:137], v[136:137], 0, s[54:55]
	global_load_lds_dwordx4 v[146:147], off
	v_lshl_add_u64 v[146:147], v[146:147], 0, s[54:55]
.Lg_ph13_noA:
	ds_read_b128 v[194:197], v142
	ds_read_b128 v[198:201], v142 offset:4096
	ds_read_b128 v[202:205], v143
	ds_read_b128 v[206:209], v143 offset:4096
	ds_read_b128 v[214:217], v144
	ds_read_b128 v[222:225], v144 offset:4096
	ds_read_b128 v[226:229], v145
	ds_read_b128 v[230:233], v145 offset:4096
	ds_read_b128 v[170:173], v138
	ds_read_b128 v[174:177], v138 offset:4096
	ds_read_b128 v[182:185], v138 offset:8192
	ds_read_b128 v[190:193], v138 offset:12288
	s_waitcnt lgkmcnt(4)
	s_barrier
	s_cmp_eq_u32 s16, 15
	s_cbranch_scc1 .Lg_ph13_noB
	s_add_i32 s58, s53, 0x10000
	s_add_i32 m0, s58, 0x0
	s_nop 0
	global_load_lds_dwordx4 v[242:243], off
	s_add_i32 m0, s58, 0x400
	v_lshl_add_u64 v[242:243], v[242:243], 0, s[54:55]
	global_load_lds_dwordx4 v[244:245], off
	s_add_i32 m0, s58, 0x2000
	v_lshl_add_u64 v[244:245], v[244:245], 0, s[54:55]
	global_load_lds_dwordx4 v[246:247], off
	s_add_i32 m0, s58, 0x2400
	v_lshl_add_u64 v[246:247], v[246:247], 0, s[54:55]
	global_load_lds_dwordx4 v[248:249], off
	v_lshl_add_u64 v[248:249], v[248:249], 0, s[54:55]
.Lg_ph13_noB:
	s_waitcnt lgkmcnt(3)
	v_mfma_f32_32x32x16_bf16 v[0:15], v[170:173], v[194:197], v[0:15]
	v_mfma_f32_32x32x16_bf16 v[16:31], v[170:173], v[198:201], v[16:31]
	ds_read_b128 v[170:173], v139
	s_waitcnt lgkmcnt(3)
	v_mfma_f32_32x32x16_bf16 v[32:47], v[174:177], v[194:197], v[32:47]
	v_mfma_f32_32x32x16_bf16 v[48:63], v[174:177], v[198:201], v[48:63]
	ds_read_b128 v[174:177], v139 offset:4096
	s_waitcnt lgkmcnt(3)
	v_mfma_f32_32x32x16_bf16 v[64:79], v[182:185], v[194:197], v[64:79]
	v_mfma_f32_32x32x16_bf16 v[80:95], v[182:185], v[198:201], v[80:95]
	ds_read_b128 v[182:185], v139 offset:8192
	s_waitcnt lgkmcnt(3)
	v_mfma_f32_32x32x16_bf16 v[96:111], v[190:193], v[194:197], v[96:111]
	v_mfma_f32_32x32x16_bf16 v[112:127], v[190:193], v[198:201], v[112:127]
	ds_read_b128 v[190:193], v139 offset:12288
	s_waitcnt lgkmcnt(3)
	v_mfma_f32_32x32x16_bf16 v[0:15], v[170:173], v[202:205], v[0:15]
	v_mfma_f32_32x32x16_bf16 v[16:31], v[170:173], v[206:209], v[16:31]
	ds_read_b128 v[170:173], v140
	s_waitcnt lgkmcnt(3)
	v_mfma_f32_32x32x16_bf16 v[32:47], v[174:177], v[202:205], v[32:47]
	v_mfma_f32_32x32x16_bf16 v[48:63], v[174:177], v[206:209], v[48:63]
	ds_read_b128 v[174:177], v140 offset:4096
	s_waitcnt lgkmcnt(3)
	v_mfma_f32_32x32x16_bf16 v[64:79], v[182:185], v[202:205], v[64:79]
	v_mfma_f32_32x32x16_bf16 v[80:95], v[182:185], v[206:209], v[80:95]
	ds_read_b128 v[182:185], v140 offset:8192
	s_waitcnt lgkmcnt(3)
	v_mfma_f32_32x32x16_bf16 v[96:111], v[190:193], v[202:205], v[96:111]
	v_mfma_f32_32x32x16_bf16 v[112:127], v[190:193], v[206:209], v[112:127]
	ds_read_b128 v[190:193], v140 offset:12288
	s_waitcnt lgkmcnt(3)
	v_mfma_f32_32x32x16_bf16 v[0:15], v[170:173], v[214:217], v[0:15]
	v_mfma_f32_32x32x16_bf16 v[16:31], v[170:173], v[222:225], v[16:31]
	ds_read_b128 v[170:173], v141
	s_waitcnt lgkmcnt(3)
	v_mfma_f32_32x32x16_bf16 v[32:47], v[174:177], v[214:217], v[32:47]
	v_mfma_f32_32x32x16_bf16 v[48:63], v[174:177], v[222:225], v[48:63]
	ds_read_b128 v[174:177], v141 offset:4096
	s_waitcnt lgkmcnt(3)
	v_mfma_f32_32x32x16_bf16 v[64:79], v[182:185], v[214:217], v[64:79]
	v_mfma_f32_32x32x16_bf16 v[80:95], v[182:185], v[222:225], v[80:95]
	ds_read_b128 v[182:185], v141 offset:8192
	s_waitcnt lgkmcnt(3)
	v_mfma_f32_32x32x16_bf16 v[96:111], v[190:193], v[214:217], v[96:111]
	v_mfma_f32_32x32x16_bf16 v[112:127], v[190:193], v[222:225], v[112:127]
	ds_read_b128 v[190:193], v141 offset:12288
	s_waitcnt lgkmcnt(3)
	v_mfma_f32_32x32x16_bf16 v[0:15], v[170:173], v[226:229], v[0:15]
	v_mfma_f32_32x32x16_bf16 v[16:31], v[170:173], v[230:233], v[16:31]
	s_waitcnt lgkmcnt(2)
	v_mfma_f32_32x32x16_bf16 v[32:47], v[174:177], v[226:229], v[32:47]
	v_mfma_f32_32x32x16_bf16 v[48:63], v[174:177], v[230:233], v[48:63]
	s_waitcnt lgkmcnt(1)
	v_mfma_f32_32x32x16_bf16 v[64:79], v[182:185], v[226:229], v[64:79]
	v_mfma_f32_32x32x16_bf16 v[80:95], v[182:185], v[230:233], v[80:95]
	s_waitcnt lgkmcnt(0)
	v_mfma_f32_32x32x16_bf16 v[96:111], v[190:193], v[226:229], v[96:111]
	v_mfma_f32_32x32x16_bf16 v[112:127], v[190:193], v[230:233], v[112:127]
	v_xor_b32_e32 v138, 0x8000, v138
	v_xor_b32_e32 v139, 0x8000, v139
	v_xor_b32_e32 v140, 0x8000, v140
	v_xor_b32_e32 v141, 0x8000, v141
	s_xor_b32 s17, s17, 0x8000
	s_add_i32 s16, s16, 1
	s_cmp_eq_u32 s16, 16
	s_cbranch_scc0 .Lg_ph13_top
	v_mov_b32_e32 v175, 0x12000
	v_mov_b32_e32 v176, s56
	v_mov_b32_e32 v177, s57
	ds_write_b64 v175, v[176:177]
	s_waitcnt vmcnt(0)
	v_mov_b32_e32 v130, v180
	v_add_u32_e32 v202, 0x400, v153
	v_add_u32_e32 v201, 0x1000, v153
	v_add_u32_e32 v200, 0x1400, v153
	v_add_u32_e32 v199, 0x2000, v153
	v_add_u32_e32 v193, 0x2400, v153
	v_add_u32_e32 v194, 0x3000, v153
	v_add_u32_e32 v195, 0x3200, v153
	v_add_u32_e32 v196, 0x3400, v153
	v_add_u32_e32 v197, 0x3600, v153
	v_add_u32_e32 v198, 0x4000, v153
	v_add_u32_e32 v190, 0x4400, v153
	v_add_u32_e32 v191, 0x4800, v153
	v_add_u32_e32 v192, 0x5000, v153
	v_add_u32_e32 v186, 0x5400, v153
	v_add_u32_e32 v187, 0x5800, v153
	v_add_u32_e32 v189, 0x6000, v153
	v_add_u32_e32 v179, 0x6400, v153
	v_add_u32_e32 v181, 0x6800, v153
	v_add_u32_e32 v182, 0x7200, v153
	v_add_u32_e32 v183, 0x7400, v153
	v_add_u32_e32 v184, 0x7600, v153
	v_add_u32_e32 v185, 0x7800, v153
	v_add_u32_e32 v178, 0x8400, v153
	v_add_u32_e32 v177, 0x8800, v153
	v_add_u32_e32 v176, 0x9400, v153
	v_add_u32_e32 v175, 0x9800, v153
	v_add_u32_e32 v174, 0xa400, v153
	v_add_u32_e32 v147, 0xa800, v153
	v_add_u32_e32 v169, 0xb400, v153
	v_add_u32_e32 v170, 0xb600, v153
	v_add_u32_e32 v171, 0xb800, v153
	v_add_u32_e32 v172, 0xba00, v153
	s_waitcnt vmcnt(0)
	s_barrier
	s_and_saveexec_b64 s[16:17], s[6:7]
	s_cbranch_execz .LBB0_1319
	v_add_u32_e32 v136, 0xc400, v153
	ds_write2_b32 v153, v0, v16 offset1:32
	ds_write2_b32 v153, v1, v17 offset0:132 offset1:164
	ds_write2_b32 v202, v2, v18 offset0:8 offset1:40
	ds_write2_b32 v202, v3, v19 offset0:140 offset1:172
	ds_write2_b32 v201, v4, v20 offset0:32 offset1:64
	ds_write2_b32 v201, v5, v21 offset0:164 offset1:196
	ds_write2_b32 v200, v6, v22 offset0:40 offset1:72
	ds_write2_b32 v200, v7, v23 offset0:172 offset1:204
	ds_write2_b32 v199, v8, v24 offset0:64 offset1:96
	ds_write2_b32 v199, v9, v25 offset0:196 offset1:228
	ds_write2_b32 v193, v10, v26 offset0:72 offset1:104
	ds_write2_b32 v193, v11, v27 offset0:204 offset1:236
	ds_write2_b32 v194, v12, v28 offset0:96 offset1:128
	ds_write2_b32 v195, v13, v29 offset0:100 offset1:132
	ds_write2_b32 v196, v14, v30 offset0:104 offset1:136
	ds_write2_b32 v197, v15, v31 offset0:108 offset1:140
	ds_write2_b32 v198, v32, v48 offset0:128 offset1:160
	ds_write2_b32 v190, v33, v49 offset0:4 offset1:36
	ds_write2_b32 v190, v34, v50 offset0:136 offset1:168
	ds_write2_b32 v191, v35, v51 offset0:12 offset1:44
	ds_write2_b32 v192, v36, v52 offset0:160 offset1:192
	ds_write2_b32 v186, v37, v53 offset0:36 offset1:68
	ds_write2_b32 v186, v38, v54 offset0:168 offset1:200
	ds_write2_b32 v187, v39, v55 offset0:44 offset1:76
	ds_write2_b32 v189, v40, v56 offset0:192 offset1:224
	ds_write2_b32 v179, v41, v57 offset0:68 offset1:100
	ds_write2_b32 v179, v42, v58 offset0:200 offset1:232
	ds_write2_b32 v181, v43, v59 offset0:76 offset1:108
	ds_write2_b32 v182, v44, v60 offset0:96 offset1:128
	ds_write2_b32 v183, v45, v61 offset0:100 offset1:132
	ds_write2_b32 v184, v46, v62 offset0:104 offset1:136
	ds_write2_b32 v185, v47, v63 offset0:108 offset1:140
	ds_write2_b32 v178, v64, v80 offset1:32
	ds_write2_b32 v178, v65, v81 offset0:132 offset1:164
	ds_write2_b32 v177, v66, v82 offset0:8 offset1:40
	ds_write2_b32 v177, v67, v83 offset0:140 offset1:172
	ds_write2_b32 v176, v68, v84 offset0:32 offset1:64
	ds_write2_b32 v176, v69, v85 offset0:164 offset1:196
	ds_write2_b32 v175, v70, v86 offset0:40 offset1:72
	ds_write2_b32 v175, v71, v87 offset0:172 offset1:204
	ds_write2_b32 v174, v72, v88 offset0:64 offset1:96
	ds_write2_b32 v174, v73, v89 offset0:196 offset1:228
	ds_write2_b32 v147, v74, v90 offset0:72 offset1:104
	ds_write2_b32 v147, v75, v91 offset0:204 offset1:236
	ds_write2_b32 v169, v76, v92 offset0:96 offset1:128
	ds_write2_b32 v170, v77, v93 offset0:100 offset1:132
	ds_write2_b32 v171, v78, v94 offset0:104 offset1:136
	ds_write2_b32 v172, v79, v95 offset0:108 offset1:140
	ds_write2_b32 v136, v96, v112 offset0:128 offset1:160
	v_add_u32_e32 v136, 0xc800, v153
	ds_write2_b32 v136, v97, v113 offset0:4 offset1:36
	ds_write2_b32 v136, v98, v114 offset0:136 offset1:168
	v_add_u32_e32 v136, 0xcc00, v153
	ds_write2_b32 v136, v99, v115 offset0:12 offset1:44
	v_add_u32_e32 v136, 0xd400, v153
	ds_write2_b32 v136, v100, v116 offset0:160 offset1:192
	v_add_u32_e32 v136, 0xd800, v153
	ds_write2_b32 v136, v101, v117 offset0:36 offset1:68
	ds_write2_b32 v136, v102, v118 offset0:168 offset1:200
	v_add_u32_e32 v136, 0xdc00, v153
	ds_write2_b32 v136, v103, v119 offset0:44 offset1:76
	v_add_u32_e32 v136, 0xe400, v153
	ds_write2_b32 v136, v104, v120 offset0:192 offset1:224
	v_add_u32_e32 v136, 0xe800, v153
	ds_write2_b32 v136, v105, v121 offset0:68 offset1:100
	ds_write2_b32 v136, v106, v122 offset0:200 offset1:232
	v_add_u32_e32 v136, 0xec00, v153
	ds_write2_b32 v136, v107, v123 offset0:76 offset1:108
	v_add_u32_e32 v136, 0xf600, v153
	ds_write2_b32 v136, v108, v124 offset0:96 offset1:128
	v_add_u32_e32 v136, 0xf800, v153
	ds_write2_b32 v136, v109, v125 offset0:100 offset1:132
	v_add_u32_e32 v136, 0xfa00, v153
	ds_write2_b32 v136, v110, v126 offset0:104 offset1:136
	v_add_u32_e32 v136, 0xfc00, v153
	ds_write2_b32 v136, v111, v127 offset0:108 offset1:140
